# LayerNorm loops: gamma/beta staged in LDS, next row prefetched a full iteration ahead into a second raw buffer (loop unrolled x2), counted vmcnt/lgkmcnt
# speedup vs baseline: 1.0171x; 1.0042x over previous
; __device__ __forceinline__ int lane_id() { int l; asm volatile("v_mbcnt_lo_u32_b32 %0, -1, 0\n\tv_mbcnt_hi_u32_b32 %0, -1, %0" : "=v"(l)); return l; }
; __device__ __forceinline__ void bf8_unpack(const u32x4 x, float (&f)[8]) { f[0] = bf_lo(x.x); f[1] = bf_hi(x.x); f[2] = bf_lo(x.y); f[3] = bf_hi(x.y); f[4] = bf_lo(x.z); f[5] = bf_hi(x.z); f[6] = bf_lo(x.w); f[7] = bf_hi(x.w); }
; template <bool FINAL>
; __device__ __forceinline__ void ln_phase(const bf16_t* pre, const float* gam, const float* bet, float* outf, bf16_t* outb, int wave) {
;     int lane_ = lane_id(); asm volatile("" : "+v"(lane_)); const int lane = lane_;
;     const int gw = blockIdx.x * 8 + wave, NGW = gridDim.x * 8;
;     for (int row = gw; row < NTOK; row += NGW) {
;         const u32x4* src = (const u32x4*)(pre + (size_t)row * DM) + lane;
;         float v[8][8]; float s = 0.f;
; #pragma unroll
;         for (int j = 0; j < 8; ++j) { const u32x4 x = src[64 * j]; bf8_unpack(x, v[j]);
;     ...
;         for (int j = 0; j < 8; ++j) {
;             const int c0 = 8 * (lane + 64 * j);
;             const f32x4 g0 = *(const f32x4*)(gam + c0), g1 = *(const f32x4*)(gam + c0 + 4), b0 = *(const f32x4*)(bet + c0), b1 = *(const f32x4*)(bet + c0 + 4);
.LBB0_1017:
	s_waitcnt lgkmcnt(0)
	s_barrier
	s_load_dwordx2 s[6:7], s[0:1], 0x50
	s_load_dwordx2 s[8:9], s[0:1], 0x58
	s_cmpk_lt_i32 s38, 0x2100
	v_mbcnt_lo_u32_b32 v0, -1, 0
	v_mbcnt_hi_u32_b32 v0, -1, v0
	s_cselect_b64 s[60:61], -1, 0
	s_cmpk_gt_i32 s38, 0x20ff
	s_cbranch_scc1 .LBB0_1020
	v_mbcnt_hi_u32_b32 v6, -1, v192
	v_and_b32_e32 v2, 64, v6
	v_add_u32_e32 v7, 64, v2
	v_xor_b32_e32 v8, 1, v6
	v_cmp_lt_i32_e32 vcc, v8, v7
	v_lshlrev_b32_e32 v2, 3, v0
	v_ashrrev_i32_e32 v3, 31, v2
	v_cndmask_b32_e32 v8, v6, v8, vcc
	v_lshlrev_b32_e32 v91, 2, v8
	v_xor_b32_e32 v8, 2, v6
	v_cmp_lt_i32_e32 vcc, v8, v7
	v_lshlrev_b64 v[4:5], 2, v[2:3]
	s_waitcnt lgkmcnt(0)
	v_mbcnt_lo_u32_b32 v248, -1, 0
	v_mbcnt_hi_u32_b32 v248, -1, v248
	v_readlane_b32 s4, v250, 0
	s_nop 1
	v_lshl_add_u32 v216, s4, 6, v248
	v_lshlrev_b32_e32 v216, 5, v216
	v_lshlrev_b32_e32 v248, 5, v248
	global_load_dwordx4 v[220:223], v216, s[6:7]
	global_load_dwordx4 v[224:227], v216, s[6:7] offset:16
	global_load_dwordx4 v[228:231], v216, s[8:9]
	global_load_dwordx4 v[232:235], v216, s[8:9] offset:16
	s_waitcnt vmcnt(0)
	ds_write_b128 v216, v[220:223]
	ds_write_b128 v216, v[224:227] offset:16
	ds_write_b128 v216, v[228:231] offset:16384
	ds_write_b128 v216, v[232:235] offset:16400
	s_waitcnt lgkmcnt(0)
	s_barrier
	v_lshl_add_u64 v[16:17], s[6:7], 0, v[4:5]
	v_cndmask_b32_e32 v8, v6, v8, vcc
	v_lshlrev_b32_e32 v92, 2, v8
	v_xor_b32_e32 v8, 4, v6
	v_cmp_lt_i32_e32 vcc, v8, v7
	v_lshl_add_u64 v[18:19], s[8:9], 0, v[4:5]
	v_add_u32_e32 v4, 0x400, v2
	v_cndmask_b32_e32 v8, v6, v8, vcc
	v_lshlrev_b32_e32 v93, 2, v8
	v_xor_b32_e32 v8, 8, v6
	v_cmp_lt_i32_e32 vcc, v8, v7
	v_ashrrev_i32_e32 v5, 31, v4
	v_lshlrev_b64 v[4:5], 2, v[4:5]
	v_cndmask_b32_e32 v8, v6, v8, vcc
	v_lshlrev_b32_e32 v94, 2, v8
	v_xor_b32_e32 v8, 16, v6
	v_cmp_lt_i32_e32 vcc, v8, v7
	v_lshl_add_u64 v[20:21], s[6:7], 0, v[4:5]
	v_lshl_add_u64 v[22:23], s[8:9], 0, v[4:5]
	v_add_u32_e32 v4, 0x600, v2
	v_cndmask_b32_e32 v8, v6, v8, vcc
	v_ashrrev_i32_e32 v5, 31, v4
	v_lshlrev_b32_e32 v95, 2, v8
	v_xor_b32_e32 v8, 32, v6
	v_lshlrev_b64 v[4:5], 2, v[4:5]
	v_cmp_lt_i32_e32 vcc, v8, v7
	v_lshl_add_u64 v[24:25], s[6:7], 0, v[4:5]
	v_lshl_add_u64 v[26:27], s[8:9], 0, v[4:5]
	v_add_u32_e32 v4, 0x800, v2
	v_cndmask_b32_e32 v6, v6, v8, vcc
	v_ashrrev_i32_e32 v5, 31, v4
	v_lshlrev_b32_e32 v96, 2, v6
	v_lshlrev_b64 v[6:7], 2, v[4:5]
	v_lshl_add_u64 v[28:29], s[6:7], 0, v[6:7]
	v_lshl_add_u64 v[30:31], s[8:9], 0, v[6:7]
	v_add_u32_e32 v6, 0xa00, v2
	v_ashrrev_i32_e32 v7, 31, v6
	v_lshlrev_b64 v[8:9], 2, v[6:7]
	v_lshl_add_u64 v[32:33], s[6:7], 0, v[8:9]
	v_lshl_add_u64 v[34:35], s[8:9], 0, v[8:9]
	v_add_u32_e32 v8, 0xc00, v2
	v_ashrrev_i32_e32 v9, 31, v8
	v_lshlrev_b64 v[10:11], 2, v[8:9]
	v_lshl_add_u64 v[36:37], s[6:7], 0, v[10:11]
	v_lshl_add_u64 v[38:39], s[8:9], 0, v[10:11]
	v_add_u32_e32 v10, 0xe00, v2
	v_ashrrev_i32_e32 v11, 31, v10
	s_ashr_i32 s39, s38, 31
	v_lshlrev_b64 v[12:13], 2, v[10:11]
	s_lshl_b64 s[4:5], s[38:39], 13
	v_lshl_add_u64 v[42:43], s[8:9], 0, v[12:13]
	s_add_u32 s8, s42, s4
	v_ashrrev_i32_e32 v1, 31, v0
	v_lshl_add_u64 v[40:41], s[6:7], 0, v[12:13]
	v_mov_b64_e32 v[12:13], 0x16400000
	s_addc_u32 s9, s43, s5
	s_ashr_i32 s41, s40, 31
	v_lshl_add_u64 v[44:45], v[10:11], 1, v[12:13]
	s_lshl_b64 s[10:11], s[40:41], 13
	v_lshl_add_u64 v[46:47], v[8:9], 1, v[12:13]
	v_lshl_add_u64 v[48:49], v[6:7], 1, v[12:13]
	v_lshl_add_u64 v[50:51], v[4:5], 1, v[12:13]
	v_lshlrev_b64 v[52:53], 1, v[2:3]
	v_lshlrev_b64 v[54:55], 4, v[0:1]
	s_mov_b32 s3, 0x24b01000
	v_mov_b32_e32 v97, 0x3727c5ac
	s_mov_b32 s4, 0xf800000
	v_mov_b32_e32 v98, 0x260
	s_mov_b32 s5, 0x16400000
	s_mov_b32 s12, s38
	s_add_u32 s6, s8, 0x24b00000
	s_addc_u32 s7, s9, 0
	global_load_dwordx4 v[216:219], v54, s[6:7]
	global_load_dwordx4 v[220:223], v54, s[6:7] offset:1024
	global_load_dwordx4 v[224:227], v54, s[6:7] offset:2048
	global_load_dwordx4 v[228:231], v54, s[6:7] offset:3072
	s_add_u32 s6, s6, 0x1000
	s_addc_u32 s7, s7, 0
	global_load_dwordx4 v[232:235], v54, s[6:7]
	global_load_dwordx4 v[236:239], v54, s[6:7] offset:1024
	global_load_dwordx4 v[240:243], v54, s[6:7] offset:2048
	global_load_dwordx4 v[244:247], v54, s[6:7] offset:3072
	s_waitcnt vmcnt(0)
.LBB0_1019:
	s_add_u32 s6, s8, s10
	s_addc_u32 s7, s9, s11
	s_add_u32 s6, s6, 0x24b00000
	s_addc_u32 s7, s7, 0
	global_load_dwordx4 v[16:19], v54, s[6:7]
	global_load_dwordx4 v[20:23], v54, s[6:7] offset:1024
	global_load_dwordx4 v[24:27], v54, s[6:7] offset:2048
	global_load_dwordx4 v[28:31], v54, s[6:7] offset:3072
	s_add_u32 s6, s6, 0x1000
	s_addc_u32 s7, s7, 0
	global_load_dwordx4 v[32:35], v54, s[6:7]
	global_load_dwordx4 v[36:39], v54, s[6:7] offset:1024
	global_load_dwordx4 v[40:43], v54, s[6:7] offset:2048
	global_load_dwordx4 v[252:255], v54, s[6:7] offset:3072
	v_lshl_add_u64 v[58:59], s[8:9], 0, v[54:55]
	v_add_co_u32_e32 v76, vcc, 0x24b00000, v58
	v_addc_co_u32_e32 v77, vcc, 0, v59, vcc
	v_add_co_u32_e32 v58, vcc, s3, v58
	v_addc_co_u32_e32 v59, vcc, 0, v59, vcc
	v_lshl_add_u64 v[56:57], s[8:9], 0, v[52:53]
	v_add_co_u32_e64 v56, s[6:7], s5, v56
	s_add_i32 s12, s12, s40
	s_nop 0
	v_addc_co_u32_e64 v57, s[6:7], 0, v57, s[6:7]
	ds_read_b128 v[4:7], v248 offset:0
	ds_read_b128 v[0:3], v248 offset:16
	ds_read_b128 v[12:15], v248 offset:16384
	ds_read_b128 v[8:11], v248 offset:16400
	ds_read_b128 v[200:203], v248 offset:18432
	ds_read_b128 v[204:207], v248 offset:2048
	ds_read_b128 v[208:211], v248 offset:2064
	ds_read_b128 v[212:215], v248 offset:18448
	s_waitcnt vmcnt(16) lgkmcnt(0)
; __device__ __forceinline__ void bf8_unpack(const u32x4 x, float (&f)[8]) { f[0] = bf_lo(x.x); f[1] = bf_hi(x.x); f[2] = bf_lo(x.y); f[3] = bf_hi(x.y); f[4] = bf_lo(x.z); f[5] = bf_hi(x.z); f[6] = bf_lo(x.w); f[7] = bf_hi(x.w); }
; template <bool FINAL>
; __device__ __forceinline__ void ln_phase(const bf16_t* pre, const float* gam, const float* bet, float* outf, bf16_t* outb, int wave) {
;     ...
;         for (int j = 0; j < 8; ++j) { const u32x4 x = src[64 * j]; bf8_unpack(x, v[j]);
; #pragma unroll
;             for (int e = 0; e < 8; ++e) s += v[j][e]; }
; #pragma unroll
;         for (int o = 1; o < 64; o <<= 1) s += __shfl_xor(s, o);
	v_lshlrev_b32_e32 v88, 16, v216
	v_and_b32_e32 v89, 0xffff0000, v216
	v_add_f32_e32 v90, 0, v88
	v_lshlrev_b32_e32 v60, 16, v217
	v_lshlrev_b32_e32 v136, 16, v244
	v_and_b32_e32 v137, 0xffff0000, v244
	v_add_f32_e32 v76, v90, v89
	v_and_b32_e32 v61, 0xffff0000, v217
	v_add_f32_e32 v76, v76, v60
	v_lshlrev_b32_e32 v58, 16, v218
	v_add_f32_e32 v76, v76, v61
	v_and_b32_e32 v59, 0xffff0000, v218
	v_add_f32_e32 v76, v76, v58
	v_lshlrev_b32_e32 v62, 16, v219
	v_add_f32_e32 v76, v76, v59
	v_and_b32_e32 v63, 0xffff0000, v219
	v_add_f32_e32 v76, v76, v62
	v_lshlrev_b32_e32 v106, 16, v220
	v_add_f32_e32 v76, v76, v63
	v_and_b32_e32 v107, 0xffff0000, v220
	v_add_f32_e32 v76, v76, v106
	v_lshlrev_b32_e32 v64, 16, v221
	v_add_f32_e32 v76, v76, v107
	v_and_b32_e32 v65, 0xffff0000, v221
	v_add_f32_e32 v76, v76, v64
	v_lshlrev_b32_e32 v104, 16, v222
	v_add_f32_e32 v76, v76, v65
	v_and_b32_e32 v105, 0xffff0000, v222
	v_add_f32_e32 v76, v76, v104
	v_lshlrev_b32_e32 v66, 16, v223
	v_add_f32_e32 v76, v76, v105
	v_and_b32_e32 v67, 0xffff0000, v223
	v_add_f32_e32 v76, v76, v66
	v_lshlrev_b32_e32 v110, 16, v224
	v_add_f32_e32 v76, v76, v67
	v_and_b32_e32 v111, 0xffff0000, v224
	v_add_f32_e32 v76, v76, v110
	v_lshlrev_b32_e32 v68, 16, v225
	v_add_f32_e32 v76, v76, v111
	v_and_b32_e32 v69, 0xffff0000, v225
	v_add_f32_e32 v76, v76, v68
	v_lshlrev_b32_e32 v108, 16, v226
	v_add_f32_e32 v76, v76, v69
	v_and_b32_e32 v109, 0xffff0000, v226
	v_add_f32_e32 v76, v76, v108
	v_lshlrev_b32_e32 v70, 16, v227
	v_add_f32_e32 v76, v76, v109
	v_and_b32_e32 v71, 0xffff0000, v227
	v_add_f32_e32 v76, v76, v70
	v_lshlrev_b32_e32 v114, 16, v228
	v_add_f32_e32 v76, v76, v71
	v_and_b32_e32 v115, 0xffff0000, v228
	v_add_f32_e32 v76, v76, v114
	v_lshlrev_b32_e32 v72, 16, v229
	v_add_f32_e32 v76, v76, v115
	v_and_b32_e32 v73, 0xffff0000, v229
	v_add_f32_e32 v76, v76, v72
	v_lshlrev_b32_e32 v112, 16, v230
	v_add_f32_e32 v76, v76, v73
	v_and_b32_e32 v113, 0xffff0000, v230
	v_add_f32_e32 v76, v76, v112
	v_lshlrev_b32_e32 v74, 16, v231
	v_add_f32_e32 v76, v76, v113
	v_and_b32_e32 v75, 0xffff0000, v231
	v_add_f32_e32 v76, v76, v74
	v_lshlrev_b32_e32 v118, 16, v234
	v_and_b32_e32 v119, 0xffff0000, v234
	v_lshlrev_b32_e32 v82, 16, v232
	v_add_f32_e32 v76, v76, v75
	v_lshlrev_b32_e32 v120, 16, v235
	v_and_b32_e32 v121, 0xffff0000, v235
	v_and_b32_e32 v83, 0xffff0000, v232
	v_add_f32_e32 v76, v76, v82
	v_lshlrev_b32_e32 v80, 16, v233
	v_add_f32_e32 v76, v76, v83
	v_and_b32_e32 v81, 0xffff0000, v233
	v_add_f32_e32 v76, v76, v80
	v_add_f32_e32 v76, v76, v81
	v_add_f32_e32 v76, v76, v118
	v_add_f32_e32 v76, v76, v119
	v_add_f32_e32 v76, v76, v120
	v_lshlrev_b32_e32 v126, 16, v236
	v_add_f32_e32 v76, v76, v121
	v_and_b32_e32 v127, 0xffff0000, v236
	v_add_f32_e32 v76, v76, v126
	v_lshlrev_b32_e32 v128, 16, v237
	v_add_f32_e32 v76, v76, v127
	v_and_b32_e32 v129, 0xffff0000, v237
	v_add_f32_e32 v76, v76, v128
	v_lshlrev_b32_e32 v122, 16, v238
	v_add_f32_e32 v76, v76, v129
	v_and_b32_e32 v123, 0xffff0000, v238
	v_add_f32_e32 v76, v76, v122
	v_lshlrev_b32_e32 v124, 16, v239
	v_add_f32_e32 v76, v76, v123
	v_and_b32_e32 v125, 0xffff0000, v239
	v_add_f32_e32 v76, v76, v124
	v_lshlrev_b32_e32 v132, 16, v240
	v_add_f32_e32 v76, v76, v125
	v_and_b32_e32 v133, 0xffff0000, v240
	v_add_f32_e32 v76, v76, v132
	v_lshlrev_b32_e32 v100, 16, v241
	v_add_f32_e32 v76, v76, v133
	v_and_b32_e32 v101, 0xffff0000, v241
	v_add_f32_e32 v76, v76, v100
	v_lshlrev_b32_e32 v130, 16, v242
	v_add_f32_e32 v76, v76, v101
	v_and_b32_e32 v131, 0xffff0000, v242
	v_add_f32_e32 v76, v76, v130
	v_lshlrev_b32_e32 v102, 16, v243
	v_add_f32_e32 v76, v76, v131
	v_and_b32_e32 v103, 0xffff0000, v243
	v_add_f32_e32 v76, v76, v102
	v_add_f32_e32 v76, v76, v103
	v_add_f32_e32 v76, v76, v136
	v_lshlrev_b32_e32 v138, 16, v245
	v_add_f32_e32 v76, v76, v137
	v_and_b32_e32 v139, 0xffff0000, v245
	v_add_f32_e32 v76, v76, v138
	v_lshlrev_b32_e32 v134, 16, v246
	v_add_f32_e32 v76, v76, v139
	v_and_b32_e32 v135, 0xffff0000, v246
	v_add_f32_e32 v76, v76, v134
	v_lshlrev_b32_e32 v117, 16, v247
	v_add_f32_e32 v76, v76, v135
	v_and_b32_e32 v116, 0xffff0000, v247
	v_add_f32_e32 v76, v76, v117
	v_add_f32_e32 v76, v76, v116
	ds_bpermute_b32 v77, v91, v76
	s_waitcnt lgkmcnt(0)
	v_add_f32_e32 v76, v76, v77
	ds_bpermute_b32 v77, v92, v76
	s_waitcnt lgkmcnt(0)
	v_add_f32_e32 v76, v76, v77
	ds_bpermute_b32 v77, v93, v76
	s_waitcnt lgkmcnt(0)
	v_add_f32_e32 v76, v76, v77
	ds_bpermute_b32 v77, v94, v76
	s_waitcnt lgkmcnt(0)
	v_add_f32_e32 v76, v76, v77
	ds_bpermute_b32 v77, v95, v76
	s_waitcnt lgkmcnt(0)
	v_add_f32_e32 v76, v76, v77
	ds_bpermute_b32 v77, v96, v76
	s_waitcnt lgkmcnt(0)
; template <bool FINAL>
; __device__ __forceinline__ void ln_phase(const bf16_t* pre, const float* gam, const float* bet, float* outf, bf16_t* outb, int wave) {
;     ...
;         const float mean = s * (1.0f / DM); float q = 0.f;
; #pragma unroll
;         for (int j = 0; j < 8; ++j)
; #pragma unroll
;             for (int e = 0; e < 8; ++e) { v[j][e] -= mean; q += v[j][e] * v[j][e]; }
; #pragma unroll
;         for (int o = 1; o < 64; o <<= 1) q += __shfl_xor(q, o);
	v_add_f32_e32 v76, v76, v77
	v_mul_f32_e32 v90, 0x39800000, v76
	v_pk_add_f32 v[140:141], v[88:89], v[90:91] op_sel_hi:[1, 0] neg_lo:[0, 1] neg_hi:[0, 1]
	v_pk_add_f32 v[142:143], v[60:61], v[90:91] op_sel_hi:[1, 0] neg_lo:[0, 1] neg_hi:[0, 1]
	v_pk_add_f32 v[152:153], v[68:69], v[90:91] op_sel_hi:[1, 0] neg_lo:[0, 1] neg_hi:[0, 1]
	v_pk_add_f32 v[68:69], v[100:101], v[90:91] op_sel_hi:[1, 0] neg_lo:[0, 1] neg_hi:[0, 1]
	v_pk_mul_f32 v[100:101], v[140:141], v[140:141]
	v_pk_add_f32 v[144:145], v[58:59], v[90:91] op_sel_hi:[1, 0] neg_lo:[0, 1] neg_hi:[0, 1]
	v_pk_add_f32 v[146:147], v[62:63], v[90:91] op_sel_hi:[1, 0] neg_lo:[0, 1] neg_hi:[0, 1]
	v_pk_add_f32 v[106:107], v[106:107], v[90:91] op_sel_hi:[1, 0] neg_lo:[0, 1] neg_hi:[0, 1]
	v_pk_add_f32 v[148:149], v[64:65], v[90:91] op_sel_hi:[1, 0] neg_lo:[0, 1] neg_hi:[0, 1]
	v_pk_add_f32 v[104:105], v[104:105], v[90:91] op_sel_hi:[1, 0] neg_lo:[0, 1] neg_hi:[0, 1]
	v_pk_add_f32 v[150:151], v[66:67], v[90:91] op_sel_hi:[1, 0] neg_lo:[0, 1] neg_hi:[0, 1]
	v_pk_add_f32 v[110:111], v[110:111], v[90:91] op_sel_hi:[1, 0] neg_lo:[0, 1] neg_hi:[0, 1]
	v_pk_add_f32 v[108:109], v[108:109], v[90:91] op_sel_hi:[1, 0] neg_lo:[0, 1] neg_hi:[0, 1]
	v_pk_add_f32 v[154:155], v[70:71], v[90:91] op_sel_hi:[1, 0] neg_lo:[0, 1] neg_hi:[0, 1]
	v_pk_add_f32 v[114:115], v[114:115], v[90:91] op_sel_hi:[1, 0] neg_lo:[0, 1] neg_hi:[0, 1]
	v_pk_add_f32 v[156:157], v[72:73], v[90:91] op_sel_hi:[1, 0] neg_lo:[0, 1] neg_hi:[0, 1]
	v_pk_add_f32 v[112:113], v[112:113], v[90:91] op_sel_hi:[1, 0] neg_lo:[0, 1] neg_hi:[0, 1]
	v_pk_add_f32 v[158:159], v[74:75], v[90:91] op_sel_hi:[1, 0] neg_lo:[0, 1] neg_hi:[0, 1]
	v_pk_add_f32 v[82:83], v[82:83], v[90:91] op_sel_hi:[1, 0] neg_lo:[0, 1] neg_hi:[0, 1]
	v_pk_add_f32 v[84:85], v[80:81], v[90:91] op_sel_hi:[1, 0] neg_lo:[0, 1] neg_hi:[0, 1]
	v_pk_add_f32 v[86:87], v[118:119], v[90:91] op_sel_hi:[1, 0] neg_lo:[0, 1] neg_hi:[0, 1]
	v_pk_add_f32 v[88:89], v[120:121], v[90:91] op_sel_hi:[1, 0] neg_lo:[0, 1] neg_hi:[0, 1]
	v_pk_add_f32 v[74:75], v[126:127], v[90:91] op_sel_hi:[1, 0] neg_lo:[0, 1] neg_hi:[0, 1]
	v_pk_add_f32 v[76:77], v[128:129], v[90:91] op_sel_hi:[1, 0] neg_lo:[0, 1] neg_hi:[0, 1]
	v_pk_add_f32 v[78:79], v[122:123], v[90:91] op_sel_hi:[1, 0] neg_lo:[0, 1] neg_hi:[0, 1]
	v_pk_add_f32 v[80:81], v[124:125], v[90:91] op_sel_hi:[1, 0] neg_lo:[0, 1] neg_hi:[0, 1]
	v_pk_add_f32 v[66:67], v[132:133], v[90:91] op_sel_hi:[1, 0] neg_lo:[0, 1] neg_hi:[0, 1]
	v_pk_add_f32 v[70:71], v[130:131], v[90:91] op_sel_hi:[1, 0] neg_lo:[0, 1] neg_hi:[0, 1]
	v_pk_add_f32 v[72:73], v[102:103], v[90:91] op_sel_hi:[1, 0] neg_lo:[0, 1] neg_hi:[0, 1]
	v_pk_add_f32 v[58:59], v[136:137], v[90:91] op_sel_hi:[1, 0] neg_lo:[0, 1] neg_hi:[0, 1]
	v_pk_add_f32 v[60:61], v[138:139], v[90:91] op_sel_hi:[1, 0] neg_lo:[0, 1] neg_hi:[0, 1]
	v_pk_add_f32 v[62:63], v[134:135], v[90:91] op_sel_hi:[1, 0] neg_lo:[0, 1] neg_hi:[0, 1]
	v_pk_add_f32 v[64:65], v[116:117], v[90:91] op_sel_hi:[1, 0] neg_lo:[0, 1] neg_hi:[0, 1]
	v_pk_mul_f32 v[102:103], v[142:143], v[142:143]
	v_add_f32_e32 v90, v100, v101
	v_add_f32_e32 v90, v102, v90
	v_pk_mul_f32 v[116:117], v[144:145], v[144:145]
	v_add_f32_e32 v90, v103, v90
	v_add_f32_e32 v90, v116, v90
	v_pk_mul_f32 v[118:119], v[146:147], v[146:147]
	v_add_f32_e32 v90, v117, v90
	v_add_f32_e32 v90, v118, v90
	v_pk_mul_f32 v[120:121], v[106:107], v[106:107]
	v_add_f32_e32 v90, v119, v90
	v_add_f32_e32 v90, v120, v90
	v_pk_mul_f32 v[122:123], v[148:149], v[148:149]
	v_add_f32_e32 v90, v121, v90
	v_add_f32_e32 v90, v122, v90
	v_pk_mul_f32 v[124:125], v[104:105], v[104:105]
	v_add_f32_e32 v90, v123, v90
	v_add_f32_e32 v90, v124, v90
	v_pk_mul_f32 v[126:127], v[150:151], v[150:151]
	v_add_f32_e32 v90, v125, v90
	v_add_f32_e32 v90, v126, v90
	v_pk_mul_f32 v[128:129], v[110:111], v[110:111]
	v_add_f32_e32 v90, v127, v90
	v_add_f32_e32 v90, v128, v90
	v_pk_mul_f32 v[130:131], v[152:153], v[152:153]
	v_add_f32_e32 v90, v129, v90
	v_add_f32_e32 v90, v130, v90
	v_pk_mul_f32 v[132:133], v[108:109], v[108:109]
	v_add_f32_e32 v90, v131, v90
	v_add_f32_e32 v90, v132, v90
	v_pk_mul_f32 v[134:135], v[154:155], v[154:155]
	v_add_f32_e32 v90, v133, v90
	v_add_f32_e32 v90, v134, v90
	v_pk_mul_f32 v[136:137], v[114:115], v[114:115]
	v_add_f32_e32 v90, v135, v90
	v_add_f32_e32 v90, v136, v90
	v_pk_mul_f32 v[138:139], v[156:157], v[156:157]
	v_add_f32_e32 v90, v137, v90
	v_add_f32_e32 v90, v138, v90
	v_pk_mul_f32 v[160:161], v[112:113], v[112:113]
	v_add_f32_e32 v90, v139, v90
	v_add_f32_e32 v90, v160, v90
	v_pk_mul_f32 v[162:163], v[158:159], v[158:159]
	v_add_f32_e32 v90, v161, v90
	v_add_f32_e32 v90, v162, v90
	v_pk_mul_f32 v[164:165], v[82:83], v[82:83]
	v_add_f32_e32 v90, v163, v90
	v_add_f32_e32 v90, v164, v90
	v_pk_mul_f32 v[166:167], v[84:85], v[84:85]
	v_add_f32_e32 v90, v165, v90
	v_add_f32_e32 v90, v166, v90
	v_pk_mul_f32 v[168:169], v[86:87], v[86:87]
	v_add_f32_e32 v90, v167, v90
	v_add_f32_e32 v90, v168, v90
	v_pk_mul_f32 v[170:171], v[88:89], v[88:89]
	v_add_f32_e32 v90, v169, v90
	v_add_f32_e32 v90, v170, v90
	v_pk_mul_f32 v[172:173], v[74:75], v[74:75]
	v_add_f32_e32 v90, v171, v90
	v_add_f32_e32 v90, v172, v90
	v_pk_mul_f32 v[174:175], v[76:77], v[76:77]
	v_add_f32_e32 v90, v173, v90
	v_add_f32_e32 v90, v174, v90
	v_pk_mul_f32 v[176:177], v[78:79], v[78:79]
	v_add_f32_e32 v90, v175, v90
	v_add_f32_e32 v90, v176, v90
	v_pk_mul_f32 v[178:179], v[80:81], v[80:81]
	v_add_f32_e32 v90, v177, v90
	v_add_f32_e32 v90, v178, v90
	v_pk_mul_f32 v[180:181], v[66:67], v[66:67]
	v_add_f32_e32 v90, v179, v90
	v_add_f32_e32 v90, v180, v90
	v_pk_mul_f32 v[182:183], v[68:69], v[68:69]
	v_add_f32_e32 v90, v181, v90
	v_add_f32_e32 v90, v182, v90
	v_pk_mul_f32 v[184:185], v[70:71], v[70:71]
	v_add_f32_e32 v90, v183, v90
	v_add_f32_e32 v90, v184, v90
	v_pk_mul_f32 v[186:187], v[72:73], v[72:73]
	v_add_f32_e32 v90, v185, v90
	v_add_f32_e32 v90, v186, v90
	v_pk_mul_f32 v[188:189], v[58:59], v[58:59]
	v_add_f32_e32 v90, v187, v90
	v_add_f32_e32 v90, v188, v90
	v_pk_mul_f32 v[190:191], v[60:61], v[60:61]
	v_add_f32_e32 v90, v189, v90
	v_add_f32_e32 v90, v190, v90
	v_pk_mul_f32 v[194:195], v[62:63], v[62:63]
	v_add_f32_e32 v90, v191, v90
	v_add_f32_e32 v90, v194, v90
	v_pk_mul_f32 v[196:197], v[64:65], v[64:65]
	v_add_f32_e32 v90, v195, v90
	v_add_f32_e32 v90, v197, v90
	v_add_f32_e32 v90, v196, v90
	ds_bpermute_b32 v99, v91, v90
	s_waitcnt lgkmcnt(0)
; __device__ __forceinline__ unsigned pk2(float lo, float hi) { const bf16x2_t v = __builtin_convertvector((f32x2_t){lo, hi}, bf16x2_t); return __builtin_bit_cast(unsigned, v); }
; template <bool FINAL>
; __device__ __forceinline__ void ln_phase(const bf16_t* pre, const float* gam, const float* bet, float* outf, bf16_t* outb, int wave) {
;     ...
;         for (int o = 1; o < 64; o <<= 1) q += __shfl_xor(q, o);
;         const float rstd = 1.0f / sqrtf(q * (1.0f / DM) + LN_EPS);
; #pragma unroll
;         for (int j = 0; j < 8; ++j) {
;             const int c0 = 8 * (lane + 64 * j);
;             const f32x4 g0 = *(const f32x4*)(gam + c0), g1 = *(const f32x4*)(gam + c0 + 4), b0 = *(const f32x4*)(bet + c0), b1 = *(const f32x4*)(bet + c0 + 4);
;             const f32x4 y0 = (f32x4){v[j][0], v[j][1], v[j][2], v[j][3]} * rstd * g0 + b0, y1 = (f32x4){v[j][4], v[j][5], v[j][6], v[j][7]} * rstd * g1 + b1;
;             if (FINAL) { float* o = outf + (size_t)row * DM + c0; *(f32x4*)o = y0; *(f32x4*)(o + 4) = y1; }
;             else { u32x4 w; w.x = pk2(y0.x, y0.y); w.y = pk2(y0.z, y0.w); w.z = pk2(y1.x, y1.y); w.w = pk2(y1.z, y1.w); *(u32x4*)(outb + (size_t)row * DM + c0) = w; }
;         }
	v_add_f32_e32 v90, v90, v99
	ds_bpermute_b32 v99, v92, v90
	s_waitcnt lgkmcnt(0)
	v_add_f32_e32 v90, v90, v99
	ds_bpermute_b32 v99, v93, v90
	s_waitcnt lgkmcnt(0)
	v_add_f32_e32 v90, v90, v99
	ds_bpermute_b32 v99, v94, v90
	s_waitcnt lgkmcnt(0)
	v_add_f32_e32 v90, v90, v99
	ds_bpermute_b32 v99, v95, v90
	s_waitcnt lgkmcnt(0)
	v_add_f32_e32 v90, v90, v99
	ds_bpermute_b32 v99, v96, v90
	s_waitcnt lgkmcnt(0)
	v_add_f32_e32 v90, v90, v99
	v_fmamk_f32 v90, v90, 0x39800000, v97
	v_mul_f32_e32 v99, 0x4f800000, v90
	v_cmp_gt_f32_e32 vcc, s4, v90
	s_nop 1
	v_cndmask_b32_e32 v90, v90, v99, vcc
	v_sqrt_f32_e32 v99, v90
	s_nop 0
	v_add_u32_e32 v100, -1, v99
	v_add_u32_e32 v101, 1, v99
	v_fma_f32 v102, -v100, v99, v90
	v_fma_f32 v103, -v101, v99, v90
	v_cmp_ge_f32_e64 s[6:7], 0, v102
	s_nop 1
	v_cndmask_b32_e64 v99, v99, v100, s[6:7]
	v_cmp_lt_f32_e64 s[6:7], 0, v103
	s_nop 1
	v_cndmask_b32_e64 v99, v99, v101, s[6:7]
	v_mul_f32_e32 v100, 0x37800000, v99
	v_cndmask_b32_e32 v99, v99, v100, vcc
	v_cmp_class_f32_e32 vcc, v90, v98
	s_nop 1
	v_cndmask_b32_e32 v90, v99, v90, vcc
	v_div_scale_f32 v99, s[6:7], v90, v90, 1.0
	v_rcp_f32_e32 v101, v99
	v_div_scale_f32 v100, vcc, 1.0, v90, 1.0
	v_fma_f32 v102, -v99, v101, 1.0
	v_fmac_f32_e32 v101, v102, v101
	v_mul_f32_e32 v102, v100, v101
	v_fma_f32 v103, -v99, v102, v100
	v_fmac_f32_e32 v102, v103, v101
	v_fma_f32 v99, -v99, v102, v100
	v_div_fmas_f32 v99, v99, v101, v102
	v_div_fixup_f32 v90, v99, v90, 1.0
	v_pk_mul_f32 v[100:101], v[140:141], v[90:91] op_sel_hi:[1, 0]
	v_pk_mul_f32 v[102:103], v[142:143], v[90:91] op_sel_hi:[1, 0]
	v_pk_mul_f32 v[116:117], v[144:145], v[90:91] op_sel_hi:[1, 0]
	v_pk_mul_f32 v[118:119], v[146:147], v[90:91] op_sel_hi:[1, 0]
	v_pk_fma_f32 v[6:7], v[6:7], v[102:103], v[14:15]
	v_pk_fma_f32 v[4:5], v[4:5], v[100:101], v[12:13]
	v_pk_fma_f32 v[10:11], v[2:3], v[118:119], v[10:11]
	v_pk_fma_f32 v[2:3], v[0:1], v[116:117], v[8:9]
	v_cvt_pk_bf16_f32 v0, v4, v5
	v_cvt_pk_bf16_f32 v1, v6, v7
	v_cvt_pk_bf16_f32 v2, v2, v3
	v_cvt_pk_bf16_f32 v3, v10, v11
	global_store_dwordx4 v[56:57], v[0:3], off
	ds_read_b128 v[0:3], v248 offset:20480
	ds_read_b128 v[4:7], v248 offset:4096
	ds_read_b128 v[8:11], v248 offset:4112
	ds_read_b128 v[12:15], v248 offset:20496
	v_pk_mul_f32 v[100:101], v[106:107], v[90:91] op_sel_hi:[1, 0]
	v_pk_mul_f32 v[102:103], v[148:149], v[90:91] op_sel_hi:[1, 0]
	v_pk_mul_f32 v[104:105], v[104:105], v[90:91] op_sel_hi:[1, 0]
	v_pk_mul_f32 v[106:107], v[150:151], v[90:91] op_sel_hi:[1, 0]
	v_pk_mul_f32 v[82:83], v[82:83], v[90:91] op_sel_hi:[1, 0]
	v_pk_mul_f32 v[84:85], v[84:85], v[90:91] op_sel_hi:[1, 0]
	v_pk_mul_f32 v[86:87], v[86:87], v[90:91] op_sel_hi:[1, 0]
	v_pk_mul_f32 v[88:89], v[88:89], v[90:91] op_sel_hi:[1, 0]
	v_pk_mul_f32 v[74:75], v[74:75], v[90:91] op_sel_hi:[1, 0]
	v_pk_mul_f32 v[76:77], v[76:77], v[90:91] op_sel_hi:[1, 0]
	v_pk_mul_f32 v[78:79], v[78:79], v[90:91] op_sel_hi:[1, 0]
	v_pk_mul_f32 v[80:81], v[80:81], v[90:91] op_sel_hi:[1, 0]
	v_pk_mul_f32 v[66:67], v[66:67], v[90:91] op_sel_hi:[1, 0]
	v_pk_mul_f32 v[68:69], v[68:69], v[90:91] op_sel_hi:[1, 0]
	v_pk_mul_f32 v[70:71], v[70:71], v[90:91] op_sel_hi:[1, 0]
	v_pk_mul_f32 v[72:73], v[72:73], v[90:91] op_sel_hi:[1, 0]
	v_pk_mul_f32 v[58:59], v[58:59], v[90:91] op_sel_hi:[1, 0]
	v_pk_mul_f32 v[60:61], v[60:61], v[90:91] op_sel_hi:[1, 0]
	v_pk_mul_f32 v[62:63], v[62:63], v[90:91] op_sel_hi:[1, 0]
	v_pk_mul_f32 v[64:65], v[64:65], v[90:91] op_sel:[1, 0] op_sel_hi:[0, 0]
	v_pk_fma_f32 v[202:203], v[206:207], v[102:103], v[202:203]
	v_pk_fma_f32 v[200:201], v[204:205], v[100:101], v[200:201]
	v_pk_fma_f32 v[204:205], v[210:211], v[106:107], v[214:215]
	v_pk_fma_f32 v[206:207], v[208:209], v[104:105], v[212:213]
	v_cvt_pk_bf16_f32 v200, v200, v201
	v_cvt_pk_bf16_f32 v201, v202, v203
	v_cvt_pk_bf16_f32 v202, v206, v207
	v_cvt_pk_bf16_f32 v203, v204, v205
	global_store_dwordx4 v[56:57], v[200:203], off offset:1024
	ds_read_b128 v[200:203], v248 offset:22528
	ds_read_b128 v[204:207], v248 offset:6144
	ds_read_b128 v[208:211], v248 offset:6160
	ds_read_b128 v[212:215], v248 offset:22544
	v_pk_mul_f32 v[100:101], v[110:111], v[90:91] op_sel_hi:[1, 0]
	v_pk_mul_f32 v[102:103], v[152:153], v[90:91] op_sel_hi:[1, 0]
	v_pk_mul_f32 v[104:105], v[108:109], v[90:91] op_sel_hi:[1, 0]
	v_pk_mul_f32 v[106:107], v[154:155], v[90:91] op_sel_hi:[1, 0]
	s_waitcnt lgkmcnt(4)
	v_pk_fma_f32 v[2:3], v[6:7], v[102:103], v[2:3]
	v_pk_fma_f32 v[0:1], v[4:5], v[100:101], v[0:1]
	v_pk_fma_f32 v[4:5], v[10:11], v[106:107], v[14:15]
	v_pk_fma_f32 v[6:7], v[8:9], v[104:105], v[12:13]
	v_cvt_pk_bf16_f32 v0, v0, v1
	v_cvt_pk_bf16_f32 v1, v2, v3
	v_cvt_pk_bf16_f32 v2, v6, v7
	v_cvt_pk_bf16_f32 v3, v4, v5
	global_store_dwordx4 v[56:57], v[0:3], off offset:2048
	ds_read_b128 v[0:3], v248 offset:24576
	ds_read_b128 v[4:7], v248 offset:8192
	ds_read_b128 v[8:11], v248 offset:8208
	ds_read_b128 v[12:15], v248 offset:24592
	v_pk_mul_f32 v[100:101], v[114:115], v[90:91] op_sel_hi:[1, 0]
	v_pk_mul_f32 v[102:103], v[156:157], v[90:91] op_sel_hi:[1, 0]
	v_pk_mul_f32 v[104:105], v[112:113], v[90:91] op_sel_hi:[1, 0]
	v_pk_mul_f32 v[106:107], v[158:159], v[90:91] op_sel_hi:[1, 0]
	s_waitcnt lgkmcnt(4)
	v_pk_fma_f32 v[202:203], v[206:207], v[102:103], v[202:203]
	v_pk_fma_f32 v[200:201], v[204:205], v[100:101], v[200:201]
	v_pk_fma_f32 v[204:205], v[210:211], v[106:107], v[214:215]
	v_pk_fma_f32 v[206:207], v[208:209], v[104:105], v[212:213]
	v_cvt_pk_bf16_f32 v200, v200, v201
	v_cvt_pk_bf16_f32 v201, v202, v203
	v_cvt_pk_bf16_f32 v202, v206, v207
	v_cvt_pk_bf16_f32 v203, v204, v205
	global_store_dwordx4 v[56:57], v[200:203], off offset:3072
	ds_read_b128 v[200:203], v248 offset:26624
	ds_read_b128 v[204:207], v248 offset:10240
	ds_read_b128 v[208:211], v248 offset:10256
	ds_read_b128 v[212:215], v248 offset:26640
	v_lshl_add_u64 v[56:57], s[8:9], 0, v[50:51]
	s_waitcnt lgkmcnt(4)
; __device__ __forceinline__ unsigned pk2(float lo, float hi) { const bf16x2_t v = __builtin_convertvector((f32x2_t){lo, hi}, bf16x2_t); return __builtin_bit_cast(unsigned, v); }
; __device__ __forceinline__ void bf8_unpack(const u32x4 x, float (&f)[8]) { f[0] = bf_lo(x.x); f[1] = bf_hi(x.x); f[2] = bf_lo(x.y); f[3] = bf_hi(x.y); f[4] = bf_lo(x.z); f[5] = bf_hi(x.z); f[6] = bf_lo(x.w); f[7] = bf_hi(x.w); }
; template <bool FINAL>
; __device__ __forceinline__ void ln_phase(const bf16_t* pre, const float* gam, const float* bet, float* outf, bf16_t* outb, int wave) {
;     ...
;     for (int row = gw; row < NTOK; row += NGW) {
;         const u32x4* src = (const u32x4*)(pre + (size_t)row * DM) + lane;
;         float v[8][8]; float s = 0.f;
; #pragma unroll
;         for (int j = 0; j < 8; ++j) { const u32x4 x = src[64 * j]; bf8_unpack(x, v[j]);
;     ...
;         for (int j = 0; j < 8; ++j) {
;             const int c0 = 8 * (lane + 64 * j);
;             const f32x4 g0 = *(const f32x4*)(gam + c0), g1 = *(const f32x4*)(gam + c0 + 4), b0 = *(const f32x4*)(bet + c0), b1 = *(const f32x4*)(bet + c0 + 4);
;             const f32x4 y0 = (f32x4){v[j][0], v[j][1], v[j][2], v[j][3]} * rstd * g0 + b0, y1 = (f32x4){v[j][4], v[j][5], v[j][6], v[j][7]} * rstd * g1 + b1;
;             if (FINAL) { float* o = outf + (size_t)row * DM + c0; *(f32x4*)o = y0; *(f32x4*)(o + 4) = y1; }
;             else { u32x4 w; w.x = pk2(y0.x, y0.y); w.y = pk2(y0.z, y0.w); w.z = pk2(y1.x, y1.y); w.w = pk2(y1.z, y1.w); *(u32x4*)(outb + (size_t)row * DM + c0) = w; }
;         }
	v_pk_fma_f32 v[2:3], v[6:7], v[84:85], v[2:3]
	v_pk_fma_f32 v[0:1], v[4:5], v[82:83], v[0:1]
	v_pk_fma_f32 v[4:5], v[10:11], v[88:89], v[14:15]
	v_pk_fma_f32 v[6:7], v[8:9], v[86:87], v[12:13]
	v_cvt_pk_bf16_f32 v0, v0, v1
	v_cvt_pk_bf16_f32 v1, v2, v3
	v_cvt_pk_bf16_f32 v2, v6, v7
	v_cvt_pk_bf16_f32 v3, v4, v5
	global_store_dwordx4 v[56:57], v[0:3], off
	ds_read_b128 v[0:3], v248 offset:28672
	ds_read_b128 v[4:7], v248 offset:12288
	ds_read_b128 v[8:11], v248 offset:12304
	ds_read_b128 v[12:15], v248 offset:28688
	v_lshl_add_u64 v[56:57], s[8:9], 0, v[48:49]
	s_waitcnt lgkmcnt(4)
	v_pk_fma_f32 v[202:203], v[206:207], v[76:77], v[202:203]
	v_pk_fma_f32 v[200:201], v[204:205], v[74:75], v[200:201]
	v_pk_fma_f32 v[204:205], v[210:211], v[80:81], v[214:215]
	v_pk_fma_f32 v[206:207], v[208:209], v[78:79], v[212:213]
	v_cvt_pk_bf16_f32 v200, v200, v201
	v_cvt_pk_bf16_f32 v201, v202, v203
	v_cvt_pk_bf16_f32 v202, v206, v207
	v_cvt_pk_bf16_f32 v203, v204, v205
	global_store_dwordx4 v[56:57], v[200:203], off
	ds_read_b128 v[200:203], v248 offset:30720
	ds_read_b128 v[204:207], v248 offset:14336
	ds_read_b128 v[208:211], v248 offset:14352
	ds_read_b128 v[212:215], v248 offset:30736
	v_lshl_add_u64 v[56:57], s[8:9], 0, v[46:47]
	s_waitcnt lgkmcnt(4)
	v_pk_fma_f32 v[2:3], v[6:7], v[68:69], v[2:3]
	v_pk_fma_f32 v[0:1], v[4:5], v[66:67], v[0:1]
	v_pk_fma_f32 v[4:5], v[10:11], v[72:73], v[14:15]
	v_pk_fma_f32 v[6:7], v[8:9], v[70:71], v[12:13]
	v_cvt_pk_bf16_f32 v0, v0, v1
	v_cvt_pk_bf16_f32 v1, v2, v3
	v_cvt_pk_bf16_f32 v2, v6, v7
	v_cvt_pk_bf16_f32 v3, v4, v5
	global_store_dwordx4 v[56:57], v[0:3], off
	v_lshl_add_u64 v[56:57], s[8:9], 0, v[44:45]
	s_add_u32 s8, s8, s10
	s_addc_u32 s9, s9, s11
	s_cmpk_lt_i32 s12, 0x2100
	s_waitcnt lgkmcnt(0)
	v_pk_fma_f32 v[202:203], v[206:207], v[60:61], v[202:203]
	v_pk_fma_f32 v[200:201], v[204:205], v[58:59], v[200:201]
	v_pk_fma_f32 v[204:205], v[210:211], v[64:65], v[214:215]
	v_pk_fma_f32 v[206:207], v[208:209], v[62:63], v[212:213]
	v_cvt_pk_bf16_f32 v200, v200, v201
	v_cvt_pk_bf16_f32 v201, v202, v203
	v_cvt_pk_bf16_f32 v202, v206, v207
	v_cvt_pk_bf16_f32 v203, v204, v205
	global_store_dwordx4 v[56:57], v[200:203], off
	s_cbranch_scc0 .Lln_exit_ln1
	s_add_u32 s6, s8, s10
	s_addc_u32 s7, s9, s11
	s_add_u32 s6, s6, 0x24b00000
	s_addc_u32 s7, s7, 0
	global_load_dwordx4 v[216:219], v54, s[6:7]
	global_load_dwordx4 v[220:223], v54, s[6:7] offset:1024
	global_load_dwordx4 v[224:227], v54, s[6:7] offset:2048
	global_load_dwordx4 v[228:231], v54, s[6:7] offset:3072
	s_add_u32 s6, s6, 0x1000
	s_addc_u32 s7, s7, 0
	global_load_dwordx4 v[232:235], v54, s[6:7]
	global_load_dwordx4 v[236:239], v54, s[6:7] offset:1024
	global_load_dwordx4 v[240:243], v54, s[6:7] offset:2048
	global_load_dwordx4 v[244:247], v54, s[6:7] offset:3072
	v_lshl_add_u64 v[58:59], s[8:9], 0, v[54:55]
	v_add_co_u32_e32 v76, vcc, 0x24b00000, v58
	v_addc_co_u32_e32 v77, vcc, 0, v59, vcc
	v_add_co_u32_e32 v58, vcc, s3, v58
	v_addc_co_u32_e32 v59, vcc, 0, v59, vcc
	v_lshl_add_u64 v[56:57], s[8:9], 0, v[52:53]
	v_add_co_u32_e64 v56, s[6:7], s5, v56
	s_add_i32 s12, s12, s40
	s_nop 0
	v_addc_co_u32_e64 v57, s[6:7], 0, v57, s[6:7]
	ds_read_b128 v[4:7], v248 offset:0
	ds_read_b128 v[0:3], v248 offset:16
	ds_read_b128 v[12:15], v248 offset:16384
	ds_read_b128 v[8:11], v248 offset:16400
	ds_read_b128 v[200:203], v248 offset:18432
	ds_read_b128 v[204:207], v248 offset:2048
	ds_read_b128 v[208:211], v248 offset:2064
	ds_read_b128 v[212:215], v248 offset:18448
	s_waitcnt vmcnt(16) lgkmcnt(0)
	v_lshlrev_b32_e32 v88, 16, v16
	v_and_b32_e32 v89, 0xffff0000, v16
	v_add_f32_e32 v90, 0, v88
	v_lshlrev_b32_e32 v60, 16, v17
	v_lshlrev_b32_e32 v136, 16, v252
	v_and_b32_e32 v137, 0xffff0000, v252
	v_add_f32_e32 v76, v90, v89
	v_and_b32_e32 v61, 0xffff0000, v17
	v_add_f32_e32 v76, v76, v60
	v_lshlrev_b32_e32 v58, 16, v18
	v_add_f32_e32 v76, v76, v61
	v_and_b32_e32 v59, 0xffff0000, v18
	v_add_f32_e32 v76, v76, v58
	v_lshlrev_b32_e32 v62, 16, v19
	v_add_f32_e32 v76, v76, v59
	v_and_b32_e32 v63, 0xffff0000, v19
	v_add_f32_e32 v76, v76, v62
	v_lshlrev_b32_e32 v106, 16, v20
	v_add_f32_e32 v76, v76, v63
	v_and_b32_e32 v107, 0xffff0000, v20
	v_add_f32_e32 v76, v76, v106
	v_lshlrev_b32_e32 v64, 16, v21
	v_add_f32_e32 v76, v76, v107
	v_and_b32_e32 v65, 0xffff0000, v21
	v_add_f32_e32 v76, v76, v64
	v_lshlrev_b32_e32 v104, 16, v22
	v_add_f32_e32 v76, v76, v65
	v_and_b32_e32 v105, 0xffff0000, v22
	v_add_f32_e32 v76, v76, v104
	v_lshlrev_b32_e32 v66, 16, v23
	v_add_f32_e32 v76, v76, v105
	v_and_b32_e32 v67, 0xffff0000, v23
	v_add_f32_e32 v76, v76, v66
	v_lshlrev_b32_e32 v110, 16, v24
	v_add_f32_e32 v76, v76, v67
	v_and_b32_e32 v111, 0xffff0000, v24
	v_add_f32_e32 v76, v76, v110
	v_lshlrev_b32_e32 v68, 16, v25
	v_add_f32_e32 v76, v76, v111
	v_and_b32_e32 v69, 0xffff0000, v25
	v_add_f32_e32 v76, v76, v68
	v_lshlrev_b32_e32 v108, 16, v26
	v_add_f32_e32 v76, v76, v69
	v_and_b32_e32 v109, 0xffff0000, v26
	v_add_f32_e32 v76, v76, v108
	v_lshlrev_b32_e32 v70, 16, v27
	v_add_f32_e32 v76, v76, v109
	v_and_b32_e32 v71, 0xffff0000, v27
	v_add_f32_e32 v76, v76, v70
	v_lshlrev_b32_e32 v114, 16, v28
	v_add_f32_e32 v76, v76, v71
	v_and_b32_e32 v115, 0xffff0000, v28
	v_add_f32_e32 v76, v76, v114
	v_lshlrev_b32_e32 v72, 16, v29
	v_add_f32_e32 v76, v76, v115
	v_and_b32_e32 v73, 0xffff0000, v29
	v_add_f32_e32 v76, v76, v72
	v_lshlrev_b32_e32 v112, 16, v30
	v_add_f32_e32 v76, v76, v73
	v_and_b32_e32 v113, 0xffff0000, v30
	v_add_f32_e32 v76, v76, v112
	v_lshlrev_b32_e32 v74, 16, v31
	v_add_f32_e32 v76, v76, v113
	v_and_b32_e32 v75, 0xffff0000, v31
	v_add_f32_e32 v76, v76, v74
	v_lshlrev_b32_e32 v118, 16, v34
; __device__ __forceinline__ void bf8_unpack(const u32x4 x, float (&f)[8]) { f[0] = bf_lo(x.x); f[1] = bf_hi(x.x); f[2] = bf_lo(x.y); f[3] = bf_hi(x.y); f[4] = bf_lo(x.z); f[5] = bf_hi(x.z); f[6] = bf_lo(x.w); f[7] = bf_hi(x.w); }
; template <bool FINAL>
; __device__ __forceinline__ void ln_phase(const bf16_t* pre, const float* gam, const float* bet, float* outf, bf16_t* outb, int wave) {
;     ...
;         for (int j = 0; j < 8; ++j) { const u32x4 x = src[64 * j]; bf8_unpack(x, v[j]);
; #pragma unroll
;             for (int e = 0; e < 8; ++e) s += v[j][e]; }
; #pragma unroll
;         for (int o = 1; o < 64; o <<= 1) s += __shfl_xor(s, o);
;         const float mean = s * (1.0f / DM); float q = 0.f;
; #pragma unroll
;         for (int j = 0; j < 8; ++j)
; #pragma unroll
;             for (int e = 0; e < 8; ++e) { v[j][e] -= mean; q += v[j][e] * v[j][e]; }
; #pragma unroll
;         for (int o = 1; o < 64; o <<= 1) q += __shfl_xor(q, o);
	v_and_b32_e32 v119, 0xffff0000, v34
	v_lshlrev_b32_e32 v82, 16, v32
	v_add_f32_e32 v76, v76, v75
	v_lshlrev_b32_e32 v120, 16, v35
	v_and_b32_e32 v121, 0xffff0000, v35
	v_and_b32_e32 v83, 0xffff0000, v32
	v_add_f32_e32 v76, v76, v82
	v_lshlrev_b32_e32 v80, 16, v33
	v_add_f32_e32 v76, v76, v83
	v_and_b32_e32 v81, 0xffff0000, v33
	v_add_f32_e32 v76, v76, v80
	v_add_f32_e32 v76, v76, v81
	v_add_f32_e32 v76, v76, v118
	v_add_f32_e32 v76, v76, v119
	v_add_f32_e32 v76, v76, v120
	v_lshlrev_b32_e32 v126, 16, v36
	v_add_f32_e32 v76, v76, v121
	v_and_b32_e32 v127, 0xffff0000, v36
	v_add_f32_e32 v76, v76, v126
	v_lshlrev_b32_e32 v128, 16, v37
	v_add_f32_e32 v76, v76, v127
	v_and_b32_e32 v129, 0xffff0000, v37
	v_add_f32_e32 v76, v76, v128
	v_lshlrev_b32_e32 v122, 16, v38
	v_add_f32_e32 v76, v76, v129
	v_and_b32_e32 v123, 0xffff0000, v38
	v_add_f32_e32 v76, v76, v122
	v_lshlrev_b32_e32 v124, 16, v39
	v_add_f32_e32 v76, v76, v123
	v_and_b32_e32 v125, 0xffff0000, v39
	v_add_f32_e32 v76, v76, v124
	v_lshlrev_b32_e32 v132, 16, v40
	v_add_f32_e32 v76, v76, v125
	v_and_b32_e32 v133, 0xffff0000, v40
	v_add_f32_e32 v76, v76, v132
	v_lshlrev_b32_e32 v100, 16, v41
	v_add_f32_e32 v76, v76, v133
	v_and_b32_e32 v101, 0xffff0000, v41
	v_add_f32_e32 v76, v76, v100
	v_lshlrev_b32_e32 v130, 16, v42
	v_add_f32_e32 v76, v76, v101
	v_and_b32_e32 v131, 0xffff0000, v42
	v_add_f32_e32 v76, v76, v130
	v_lshlrev_b32_e32 v102, 16, v43
	v_add_f32_e32 v76, v76, v131
	v_and_b32_e32 v103, 0xffff0000, v43
	v_add_f32_e32 v76, v76, v102
	v_add_f32_e32 v76, v76, v103
	v_add_f32_e32 v76, v76, v136
	v_lshlrev_b32_e32 v138, 16, v253
	v_add_f32_e32 v76, v76, v137
	v_and_b32_e32 v139, 0xffff0000, v253
	v_add_f32_e32 v76, v76, v138
	v_lshlrev_b32_e32 v134, 16, v254
	v_add_f32_e32 v76, v76, v139
	v_and_b32_e32 v135, 0xffff0000, v254
	v_add_f32_e32 v76, v76, v134
	v_lshlrev_b32_e32 v117, 16, v255
	v_add_f32_e32 v76, v76, v135
	v_and_b32_e32 v116, 0xffff0000, v255
	v_add_f32_e32 v76, v76, v117
	v_add_f32_e32 v76, v76, v116
	ds_bpermute_b32 v77, v91, v76
	s_waitcnt lgkmcnt(0)
	v_add_f32_e32 v76, v76, v77
	ds_bpermute_b32 v77, v92, v76
	s_waitcnt lgkmcnt(0)
	v_add_f32_e32 v76, v76, v77
	ds_bpermute_b32 v77, v93, v76
	s_waitcnt lgkmcnt(0)
	v_add_f32_e32 v76, v76, v77
	ds_bpermute_b32 v77, v94, v76
	s_waitcnt lgkmcnt(0)
	v_add_f32_e32 v76, v76, v77
	ds_bpermute_b32 v77, v95, v76
	s_waitcnt lgkmcnt(0)
	v_add_f32_e32 v76, v76, v77
	ds_bpermute_b32 v77, v96, v76
	s_waitcnt lgkmcnt(0)
	v_add_f32_e32 v76, v76, v77
	v_mul_f32_e32 v90, 0x39800000, v76
	v_pk_add_f32 v[140:141], v[88:89], v[90:91] op_sel_hi:[1, 0] neg_lo:[0, 1] neg_hi:[0, 1]
	v_pk_add_f32 v[142:143], v[60:61], v[90:91] op_sel_hi:[1, 0] neg_lo:[0, 1] neg_hi:[0, 1]
	v_pk_add_f32 v[152:153], v[68:69], v[90:91] op_sel_hi:[1, 0] neg_lo:[0, 1] neg_hi:[0, 1]
	v_pk_add_f32 v[68:69], v[100:101], v[90:91] op_sel_hi:[1, 0] neg_lo:[0, 1] neg_hi:[0, 1]
	v_pk_mul_f32 v[100:101], v[140:141], v[140:141]
	v_pk_add_f32 v[144:145], v[58:59], v[90:91] op_sel_hi:[1, 0] neg_lo:[0, 1] neg_hi:[0, 1]
	v_pk_add_f32 v[146:147], v[62:63], v[90:91] op_sel_hi:[1, 0] neg_lo:[0, 1] neg_hi:[0, 1]
	v_pk_add_f32 v[106:107], v[106:107], v[90:91] op_sel_hi:[1, 0] neg_lo:[0, 1] neg_hi:[0, 1]
	v_pk_add_f32 v[148:149], v[64:65], v[90:91] op_sel_hi:[1, 0] neg_lo:[0, 1] neg_hi:[0, 1]
	v_pk_add_f32 v[104:105], v[104:105], v[90:91] op_sel_hi:[1, 0] neg_lo:[0, 1] neg_hi:[0, 1]
	v_pk_add_f32 v[150:151], v[66:67], v[90:91] op_sel_hi:[1, 0] neg_lo:[0, 1] neg_hi:[0, 1]
	v_pk_add_f32 v[110:111], v[110:111], v[90:91] op_sel_hi:[1, 0] neg_lo:[0, 1] neg_hi:[0, 1]
	v_pk_add_f32 v[108:109], v[108:109], v[90:91] op_sel_hi:[1, 0] neg_lo:[0, 1] neg_hi:[0, 1]
	v_pk_add_f32 v[154:155], v[70:71], v[90:91] op_sel_hi:[1, 0] neg_lo:[0, 1] neg_hi:[0, 1]
	v_pk_add_f32 v[114:115], v[114:115], v[90:91] op_sel_hi:[1, 0] neg_lo:[0, 1] neg_hi:[0, 1]
	v_pk_add_f32 v[156:157], v[72:73], v[90:91] op_sel_hi:[1, 0] neg_lo:[0, 1] neg_hi:[0, 1]
	v_pk_add_f32 v[112:113], v[112:113], v[90:91] op_sel_hi:[1, 0] neg_lo:[0, 1] neg_hi:[0, 1]
	v_pk_add_f32 v[158:159], v[74:75], v[90:91] op_sel_hi:[1, 0] neg_lo:[0, 1] neg_hi:[0, 1]
	v_pk_add_f32 v[82:83], v[82:83], v[90:91] op_sel_hi:[1, 0] neg_lo:[0, 1] neg_hi:[0, 1]
	v_pk_add_f32 v[84:85], v[80:81], v[90:91] op_sel_hi:[1, 0] neg_lo:[0, 1] neg_hi:[0, 1]
	v_pk_add_f32 v[86:87], v[118:119], v[90:91] op_sel_hi:[1, 0] neg_lo:[0, 1] neg_hi:[0, 1]
	v_pk_add_f32 v[88:89], v[120:121], v[90:91] op_sel_hi:[1, 0] neg_lo:[0, 1] neg_hi:[0, 1]
	v_pk_add_f32 v[74:75], v[126:127], v[90:91] op_sel_hi:[1, 0] neg_lo:[0, 1] neg_hi:[0, 1]
	v_pk_add_f32 v[76:77], v[128:129], v[90:91] op_sel_hi:[1, 0] neg_lo:[0, 1] neg_hi:[0, 1]
	v_pk_add_f32 v[78:79], v[122:123], v[90:91] op_sel_hi:[1, 0] neg_lo:[0, 1] neg_hi:[0, 1]
	v_pk_add_f32 v[80:81], v[124:125], v[90:91] op_sel_hi:[1, 0] neg_lo:[0, 1] neg_hi:[0, 1]
	v_pk_add_f32 v[66:67], v[132:133], v[90:91] op_sel_hi:[1, 0] neg_lo:[0, 1] neg_hi:[0, 1]
	v_pk_add_f32 v[70:71], v[130:131], v[90:91] op_sel_hi:[1, 0] neg_lo:[0, 1] neg_hi:[0, 1]
	v_pk_add_f32 v[72:73], v[102:103], v[90:91] op_sel_hi:[1, 0] neg_lo:[0, 1] neg_hi:[0, 1]
	v_pk_add_f32 v[58:59], v[136:137], v[90:91] op_sel_hi:[1, 0] neg_lo:[0, 1] neg_hi:[0, 1]
	v_pk_add_f32 v[60:61], v[138:139], v[90:91] op_sel_hi:[1, 0] neg_lo:[0, 1] neg_hi:[0, 1]
	v_pk_add_f32 v[62:63], v[134:135], v[90:91] op_sel_hi:[1, 0] neg_lo:[0, 1] neg_hi:[0, 1]
	v_pk_add_f32 v[64:65], v[116:117], v[90:91] op_sel_hi:[1, 0] neg_lo:[0, 1] neg_hi:[0, 1]
	v_pk_mul_f32 v[102:103], v[142:143], v[142:143]
	v_add_f32_e32 v90, v100, v101
	v_add_f32_e32 v90, v102, v90
	v_pk_mul_f32 v[116:117], v[144:145], v[144:145]
; __device__ __forceinline__ unsigned pk2(float lo, float hi) { const bf16x2_t v = __builtin_convertvector((f32x2_t){lo, hi}, bf16x2_t); return __builtin_bit_cast(unsigned, v); }
; template <bool FINAL>
; __device__ __forceinline__ void ln_phase(const bf16_t* pre, const float* gam, const float* bet, float* outf, bf16_t* outb, int wave) {
;     ...
;         const float mean = s * (1.0f / DM); float q = 0.f;
; #pragma unroll
;         for (int j = 0; j < 8; ++j)
; #pragma unroll
;             for (int e = 0; e < 8; ++e) { v[j][e] -= mean; q += v[j][e] * v[j][e]; }
; #pragma unroll
;         for (int o = 1; o < 64; o <<= 1) q += __shfl_xor(q, o);
;         const float rstd = 1.0f / sqrtf(q * (1.0f / DM) + LN_EPS);
; #pragma unroll
;         for (int j = 0; j < 8; ++j) {
;             const int c0 = 8 * (lane + 64 * j);
;             const f32x4 g0 = *(const f32x4*)(gam + c0), g1 = *(const f32x4*)(gam + c0 + 4), b0 = *(const f32x4*)(bet + c0), b1 = *(const f32x4*)(bet + c0 + 4);
;             const f32x4 y0 = (f32x4){v[j][0], v[j][1], v[j][2], v[j][3]} * rstd * g0 + b0, y1 = (f32x4){v[j][4], v[j][5], v[j][6], v[j][7]} * rstd * g1 + b1;
;             if (FINAL) { float* o = outf + (size_t)row * DM + c0; *(f32x4*)o = y0; *(f32x4*)(o + 4) = y1; }
;             else { u32x4 w; w.x = pk2(y0.x, y0.y); w.y = pk2(y0.z, y0.w); w.z = pk2(y1.x, y1.y); w.w = pk2(y1.z, y1.w); *(u32x4*)(outb + (size_t)row * DM + c0) = w; }
;         }
	v_add_f32_e32 v90, v103, v90
	v_add_f32_e32 v90, v116, v90
	v_pk_mul_f32 v[118:119], v[146:147], v[146:147]
	v_add_f32_e32 v90, v117, v90
	v_add_f32_e32 v90, v118, v90
	v_pk_mul_f32 v[120:121], v[106:107], v[106:107]
	v_add_f32_e32 v90, v119, v90
	v_add_f32_e32 v90, v120, v90
	v_pk_mul_f32 v[122:123], v[148:149], v[148:149]
	v_add_f32_e32 v90, v121, v90
	v_add_f32_e32 v90, v122, v90
	v_pk_mul_f32 v[124:125], v[104:105], v[104:105]
	v_add_f32_e32 v90, v123, v90
	v_add_f32_e32 v90, v124, v90
	v_pk_mul_f32 v[126:127], v[150:151], v[150:151]
	v_add_f32_e32 v90, v125, v90
	v_add_f32_e32 v90, v126, v90
	v_pk_mul_f32 v[128:129], v[110:111], v[110:111]
	v_add_f32_e32 v90, v127, v90
	v_add_f32_e32 v90, v128, v90
	v_pk_mul_f32 v[130:131], v[152:153], v[152:153]
	v_add_f32_e32 v90, v129, v90
	v_add_f32_e32 v90, v130, v90
	v_pk_mul_f32 v[132:133], v[108:109], v[108:109]
	v_add_f32_e32 v90, v131, v90
	v_add_f32_e32 v90, v132, v90
	v_pk_mul_f32 v[134:135], v[154:155], v[154:155]
	v_add_f32_e32 v90, v133, v90
	v_add_f32_e32 v90, v134, v90
	v_pk_mul_f32 v[136:137], v[114:115], v[114:115]
	v_add_f32_e32 v90, v135, v90
	v_add_f32_e32 v90, v136, v90
	v_pk_mul_f32 v[138:139], v[156:157], v[156:157]
	v_add_f32_e32 v90, v137, v90
	v_add_f32_e32 v90, v138, v90
	v_pk_mul_f32 v[160:161], v[112:113], v[112:113]
	v_add_f32_e32 v90, v139, v90
	v_add_f32_e32 v90, v160, v90
	v_pk_mul_f32 v[162:163], v[158:159], v[158:159]
	v_add_f32_e32 v90, v161, v90
	v_add_f32_e32 v90, v162, v90
	v_pk_mul_f32 v[164:165], v[82:83], v[82:83]
	v_add_f32_e32 v90, v163, v90
	v_add_f32_e32 v90, v164, v90
	v_pk_mul_f32 v[166:167], v[84:85], v[84:85]
	v_add_f32_e32 v90, v165, v90
	v_add_f32_e32 v90, v166, v90
	v_pk_mul_f32 v[168:169], v[86:87], v[86:87]
	v_add_f32_e32 v90, v167, v90
	v_add_f32_e32 v90, v168, v90
	v_pk_mul_f32 v[170:171], v[88:89], v[88:89]
	v_add_f32_e32 v90, v169, v90
	v_add_f32_e32 v90, v170, v90
	v_pk_mul_f32 v[172:173], v[74:75], v[74:75]
	v_add_f32_e32 v90, v171, v90
	v_add_f32_e32 v90, v172, v90
	v_pk_mul_f32 v[174:175], v[76:77], v[76:77]
	v_add_f32_e32 v90, v173, v90
	v_add_f32_e32 v90, v174, v90
	v_pk_mul_f32 v[176:177], v[78:79], v[78:79]
	v_add_f32_e32 v90, v175, v90
	v_add_f32_e32 v90, v176, v90
	v_pk_mul_f32 v[178:179], v[80:81], v[80:81]
	v_add_f32_e32 v90, v177, v90
	v_add_f32_e32 v90, v178, v90
	v_pk_mul_f32 v[180:181], v[66:67], v[66:67]
	v_add_f32_e32 v90, v179, v90
	v_add_f32_e32 v90, v180, v90
	v_pk_mul_f32 v[182:183], v[68:69], v[68:69]
	v_add_f32_e32 v90, v181, v90
	v_add_f32_e32 v90, v182, v90
	v_pk_mul_f32 v[184:185], v[70:71], v[70:71]
	v_add_f32_e32 v90, v183, v90
	v_add_f32_e32 v90, v184, v90
	v_pk_mul_f32 v[186:187], v[72:73], v[72:73]
	v_add_f32_e32 v90, v185, v90
	v_add_f32_e32 v90, v186, v90
	v_pk_mul_f32 v[188:189], v[58:59], v[58:59]
	v_add_f32_e32 v90, v187, v90
	v_add_f32_e32 v90, v188, v90
	v_pk_mul_f32 v[190:191], v[60:61], v[60:61]
	v_add_f32_e32 v90, v189, v90
	v_add_f32_e32 v90, v190, v90
	v_pk_mul_f32 v[194:195], v[62:63], v[62:63]
	v_add_f32_e32 v90, v191, v90
	v_add_f32_e32 v90, v194, v90
	v_pk_mul_f32 v[196:197], v[64:65], v[64:65]
	v_add_f32_e32 v90, v195, v90
	v_add_f32_e32 v90, v197, v90
	v_add_f32_e32 v90, v196, v90
	ds_bpermute_b32 v99, v91, v90
	s_waitcnt lgkmcnt(0)
	v_add_f32_e32 v90, v90, v99
	ds_bpermute_b32 v99, v92, v90
	s_waitcnt lgkmcnt(0)
	v_add_f32_e32 v90, v90, v99
	ds_bpermute_b32 v99, v93, v90
	s_waitcnt lgkmcnt(0)
	v_add_f32_e32 v90, v90, v99
	ds_bpermute_b32 v99, v94, v90
	s_waitcnt lgkmcnt(0)
	v_add_f32_e32 v90, v90, v99
	ds_bpermute_b32 v99, v95, v90
	s_waitcnt lgkmcnt(0)
	v_add_f32_e32 v90, v90, v99
	ds_bpermute_b32 v99, v96, v90
	s_waitcnt lgkmcnt(0)
	v_add_f32_e32 v90, v90, v99
	v_fmamk_f32 v90, v90, 0x39800000, v97
	v_mul_f32_e32 v99, 0x4f800000, v90
	v_cmp_gt_f32_e32 vcc, s4, v90
	s_nop 1
	v_cndmask_b32_e32 v90, v90, v99, vcc
	v_sqrt_f32_e32 v99, v90
	s_nop 0
	v_add_u32_e32 v100, -1, v99
	v_add_u32_e32 v101, 1, v99
	v_fma_f32 v102, -v100, v99, v90
	v_fma_f32 v103, -v101, v99, v90
	v_cmp_ge_f32_e64 s[6:7], 0, v102
	s_nop 1
	v_cndmask_b32_e64 v99, v99, v100, s[6:7]
	v_cmp_lt_f32_e64 s[6:7], 0, v103
	s_nop 1
	v_cndmask_b32_e64 v99, v99, v101, s[6:7]
	v_mul_f32_e32 v100, 0x37800000, v99
	v_cndmask_b32_e32 v99, v99, v100, vcc
	v_cmp_class_f32_e32 vcc, v90, v98
	s_nop 1
	v_cndmask_b32_e32 v90, v99, v90, vcc
	v_div_scale_f32 v99, s[6:7], v90, v90, 1.0
	v_rcp_f32_e32 v101, v99
	v_div_scale_f32 v100, vcc, 1.0, v90, 1.0
	v_fma_f32 v102, -v99, v101, 1.0
	v_fmac_f32_e32 v101, v102, v101
	v_mul_f32_e32 v102, v100, v101
	v_fma_f32 v103, -v99, v102, v100
	v_fmac_f32_e32 v102, v103, v101
	v_fma_f32 v99, -v99, v102, v100
	v_div_fmas_f32 v99, v99, v101, v102
	v_div_fixup_f32 v90, v99, v90, 1.0
	v_pk_mul_f32 v[100:101], v[140:141], v[90:91] op_sel_hi:[1, 0]
	v_pk_mul_f32 v[102:103], v[142:143], v[90:91] op_sel_hi:[1, 0]
	v_pk_mul_f32 v[116:117], v[144:145], v[90:91] op_sel_hi:[1, 0]
	v_pk_mul_f32 v[118:119], v[146:147], v[90:91] op_sel_hi:[1, 0]
	v_pk_fma_f32 v[6:7], v[6:7], v[102:103], v[14:15]
	v_pk_fma_f32 v[4:5], v[4:5], v[100:101], v[12:13]
	v_pk_fma_f32 v[10:11], v[2:3], v[118:119], v[10:11]
	v_pk_fma_f32 v[2:3], v[0:1], v[116:117], v[8:9]
	v_cvt_pk_bf16_f32 v0, v4, v5
	v_cvt_pk_bf16_f32 v1, v6, v7
	v_cvt_pk_bf16_f32 v2, v2, v3
	v_cvt_pk_bf16_f32 v3, v10, v11
	global_store_dwordx4 v[56:57], v[0:3], off
	ds_read_b128 v[0:3], v248 offset:20480
	ds_read_b128 v[4:7], v248 offset:4096
	ds_read_b128 v[8:11], v248 offset:4112
	ds_read_b128 v[12:15], v248 offset:20496
	v_pk_mul_f32 v[100:101], v[106:107], v[90:91] op_sel_hi:[1, 0]
	v_pk_mul_f32 v[102:103], v[148:149], v[90:91] op_sel_hi:[1, 0]
; __device__ __forceinline__ unsigned pk2(float lo, float hi) { const bf16x2_t v = __builtin_convertvector((f32x2_t){lo, hi}, bf16x2_t); return __builtin_bit_cast(unsigned, v); }
; template <bool FINAL>
; __device__ __forceinline__ void ln_phase(const bf16_t* pre, const float* gam, const float* bet, float* outf, bf16_t* outb, int wave) {
;     ...
;         for (int j = 0; j < 8; ++j) {
;             const int c0 = 8 * (lane + 64 * j);
;             const f32x4 g0 = *(const f32x4*)(gam + c0), g1 = *(const f32x4*)(gam + c0 + 4), b0 = *(const f32x4*)(bet + c0), b1 = *(const f32x4*)(bet + c0 + 4);
;             const f32x4 y0 = (f32x4){v[j][0], v[j][1], v[j][2], v[j][3]} * rstd * g0 + b0, y1 = (f32x4){v[j][4], v[j][5], v[j][6], v[j][7]} * rstd * g1 + b1;
;             if (FINAL) { float* o = outf + (size_t)row * DM + c0; *(f32x4*)o = y0; *(f32x4*)(o + 4) = y1; }
;             else { u32x4 w; w.x = pk2(y0.x, y0.y); w.y = pk2(y0.z, y0.w); w.z = pk2(y1.x, y1.y); w.w = pk2(y1.z, y1.w); *(u32x4*)(outb + (size_t)row * DM + c0) = w; }
;         }
	v_pk_mul_f32 v[104:105], v[104:105], v[90:91] op_sel_hi:[1, 0]
	v_pk_mul_f32 v[106:107], v[150:151], v[90:91] op_sel_hi:[1, 0]
	v_pk_mul_f32 v[82:83], v[82:83], v[90:91] op_sel_hi:[1, 0]
	v_pk_mul_f32 v[84:85], v[84:85], v[90:91] op_sel_hi:[1, 0]
	v_pk_mul_f32 v[86:87], v[86:87], v[90:91] op_sel_hi:[1, 0]
	v_pk_mul_f32 v[88:89], v[88:89], v[90:91] op_sel_hi:[1, 0]
	v_pk_mul_f32 v[74:75], v[74:75], v[90:91] op_sel_hi:[1, 0]
	v_pk_mul_f32 v[76:77], v[76:77], v[90:91] op_sel_hi:[1, 0]
	v_pk_mul_f32 v[78:79], v[78:79], v[90:91] op_sel_hi:[1, 0]
	v_pk_mul_f32 v[80:81], v[80:81], v[90:91] op_sel_hi:[1, 0]
	v_pk_mul_f32 v[66:67], v[66:67], v[90:91] op_sel_hi:[1, 0]
	v_pk_mul_f32 v[68:69], v[68:69], v[90:91] op_sel_hi:[1, 0]
	v_pk_mul_f32 v[70:71], v[70:71], v[90:91] op_sel_hi:[1, 0]
	v_pk_mul_f32 v[72:73], v[72:73], v[90:91] op_sel_hi:[1, 0]
	v_pk_mul_f32 v[58:59], v[58:59], v[90:91] op_sel_hi:[1, 0]
	v_pk_mul_f32 v[60:61], v[60:61], v[90:91] op_sel_hi:[1, 0]
	v_pk_mul_f32 v[62:63], v[62:63], v[90:91] op_sel_hi:[1, 0]
	v_pk_mul_f32 v[64:65], v[64:65], v[90:91] op_sel:[1, 0] op_sel_hi:[0, 0]
	v_pk_fma_f32 v[202:203], v[206:207], v[102:103], v[202:203]
	v_pk_fma_f32 v[200:201], v[204:205], v[100:101], v[200:201]
	v_pk_fma_f32 v[204:205], v[210:211], v[106:107], v[214:215]
	v_pk_fma_f32 v[206:207], v[208:209], v[104:105], v[212:213]
	v_cvt_pk_bf16_f32 v200, v200, v201
	v_cvt_pk_bf16_f32 v201, v202, v203
	v_cvt_pk_bf16_f32 v202, v206, v207
	v_cvt_pk_bf16_f32 v203, v204, v205
	global_store_dwordx4 v[56:57], v[200:203], off offset:1024
	ds_read_b128 v[200:203], v248 offset:22528
	ds_read_b128 v[204:207], v248 offset:6144
	ds_read_b128 v[208:211], v248 offset:6160
	ds_read_b128 v[212:215], v248 offset:22544
	v_pk_mul_f32 v[100:101], v[110:111], v[90:91] op_sel_hi:[1, 0]
	v_pk_mul_f32 v[102:103], v[152:153], v[90:91] op_sel_hi:[1, 0]
	v_pk_mul_f32 v[104:105], v[108:109], v[90:91] op_sel_hi:[1, 0]
	v_pk_mul_f32 v[106:107], v[154:155], v[90:91] op_sel_hi:[1, 0]
	s_waitcnt lgkmcnt(4)
	v_pk_fma_f32 v[2:3], v[6:7], v[102:103], v[2:3]
	v_pk_fma_f32 v[0:1], v[4:5], v[100:101], v[0:1]
	v_pk_fma_f32 v[4:5], v[10:11], v[106:107], v[14:15]
	v_pk_fma_f32 v[6:7], v[8:9], v[104:105], v[12:13]
	v_cvt_pk_bf16_f32 v0, v0, v1
	v_cvt_pk_bf16_f32 v1, v2, v3
	v_cvt_pk_bf16_f32 v2, v6, v7
	v_cvt_pk_bf16_f32 v3, v4, v5
	global_store_dwordx4 v[56:57], v[0:3], off offset:2048
	ds_read_b128 v[0:3], v248 offset:24576
	ds_read_b128 v[4:7], v248 offset:8192
	ds_read_b128 v[8:11], v248 offset:8208
	ds_read_b128 v[12:15], v248 offset:24592
	v_pk_mul_f32 v[100:101], v[114:115], v[90:91] op_sel_hi:[1, 0]
	v_pk_mul_f32 v[102:103], v[156:157], v[90:91] op_sel_hi:[1, 0]
	v_pk_mul_f32 v[104:105], v[112:113], v[90:91] op_sel_hi:[1, 0]
	v_pk_mul_f32 v[106:107], v[158:159], v[90:91] op_sel_hi:[1, 0]
	s_waitcnt lgkmcnt(4)
	v_pk_fma_f32 v[202:203], v[206:207], v[102:103], v[202:203]
	v_pk_fma_f32 v[200:201], v[204:205], v[100:101], v[200:201]
	v_pk_fma_f32 v[204:205], v[210:211], v[106:107], v[214:215]
	v_pk_fma_f32 v[206:207], v[208:209], v[104:105], v[212:213]
	v_cvt_pk_bf16_f32 v200, v200, v201
	v_cvt_pk_bf16_f32 v201, v202, v203
	v_cvt_pk_bf16_f32 v202, v206, v207
	v_cvt_pk_bf16_f32 v203, v204, v205
	global_store_dwordx4 v[56:57], v[200:203], off offset:3072
	ds_read_b128 v[200:203], v248 offset:26624
	ds_read_b128 v[204:207], v248 offset:10240
	ds_read_b128 v[208:211], v248 offset:10256
	ds_read_b128 v[212:215], v248 offset:26640
	v_lshl_add_u64 v[56:57], s[8:9], 0, v[50:51]
	s_waitcnt lgkmcnt(4)
	v_pk_fma_f32 v[2:3], v[6:7], v[84:85], v[2:3]
	v_pk_fma_f32 v[0:1], v[4:5], v[82:83], v[0:1]
	v_pk_fma_f32 v[4:5], v[10:11], v[88:89], v[14:15]
	v_pk_fma_f32 v[6:7], v[8:9], v[86:87], v[12:13]
	v_cvt_pk_bf16_f32 v0, v0, v1
	v_cvt_pk_bf16_f32 v1, v2, v3
	v_cvt_pk_bf16_f32 v2, v6, v7
	v_cvt_pk_bf16_f32 v3, v4, v5
	global_store_dwordx4 v[56:57], v[0:3], off
	ds_read_b128 v[0:3], v248 offset:28672
	ds_read_b128 v[4:7], v248 offset:12288
	ds_read_b128 v[8:11], v248 offset:12304
	ds_read_b128 v[12:15], v248 offset:28688
	v_lshl_add_u64 v[56:57], s[8:9], 0, v[48:49]
	s_waitcnt lgkmcnt(4)
	v_pk_fma_f32 v[202:203], v[206:207], v[76:77], v[202:203]
	v_pk_fma_f32 v[200:201], v[204:205], v[74:75], v[200:201]
	v_pk_fma_f32 v[204:205], v[210:211], v[80:81], v[214:215]
	v_pk_fma_f32 v[206:207], v[208:209], v[78:79], v[212:213]
	v_cvt_pk_bf16_f32 v200, v200, v201
	v_cvt_pk_bf16_f32 v201, v202, v203
	v_cvt_pk_bf16_f32 v202, v206, v207
	v_cvt_pk_bf16_f32 v203, v204, v205
	global_store_dwordx4 v[56:57], v[200:203], off
	ds_read_b128 v[200:203], v248 offset:30720
	ds_read_b128 v[204:207], v248 offset:14336
	ds_read_b128 v[208:211], v248 offset:14352
	ds_read_b128 v[212:215], v248 offset:30736
	v_lshl_add_u64 v[56:57], s[8:9], 0, v[46:47]
	s_waitcnt lgkmcnt(4)
	v_pk_fma_f32 v[2:3], v[6:7], v[68:69], v[2:3]
	v_pk_fma_f32 v[0:1], v[4:5], v[66:67], v[0:1]
	v_pk_fma_f32 v[4:5], v[10:11], v[72:73], v[14:15]
	v_pk_fma_f32 v[6:7], v[8:9], v[70:71], v[12:13]
	v_cvt_pk_bf16_f32 v0, v0, v1
	v_cvt_pk_bf16_f32 v1, v2, v3
	v_cvt_pk_bf16_f32 v2, v6, v7
	v_cvt_pk_bf16_f32 v3, v4, v5
	global_store_dwordx4 v[56:57], v[0:3], off
	v_lshl_add_u64 v[56:57], s[8:9], 0, v[44:45]
	s_add_u32 s8, s8, s10
	s_addc_u32 s9, s9, s11
	s_cmpk_lt_i32 s12, 0x2100
	s_waitcnt lgkmcnt(0)
	v_pk_fma_f32 v[202:203], v[206:207], v[60:61], v[202:203]
	v_pk_fma_f32 v[200:201], v[204:205], v[58:59], v[200:201]
	v_pk_fma_f32 v[204:205], v[210:211], v[64:65], v[214:215]
	v_pk_fma_f32 v[206:207], v[208:209], v[62:63], v[212:213]
	v_cvt_pk_bf16_f32 v200, v200, v201
	v_cvt_pk_bf16_f32 v201, v202, v203
	v_cvt_pk_bf16_f32 v202, v206, v207
	v_cvt_pk_bf16_f32 v203, v204, v205
	global_store_dwordx4 v[56:57], v[200:203], off
	s_cbranch_scc1 .LBB0_1019
; #define LAS __attribute__((address_space(3)))
; __device__ __forceinline__ int lane_id() { int l; asm volatile("v_mbcnt_lo_u32_b32 %0, -1, 0\n\tv_mbcnt_hi_u32_b32 %0, -1, %0" : "=v"(l)); return l; }
; __device__ __forceinline__ unsigned xb_ld(unsigned* p)              { return __hip_atomic_load(p, __ATOMIC_RELAXED, __HIP_MEMORY_SCOPE_AGENT); }
; __device__ __forceinline__ unsigned xb_xcc_id() { return (unsigned)__builtin_amdgcn_s_getreg((3 << 11) | 20) & 0xFu; }
; __device__ __forceinline__ void xcd_barrier_complete(unsigned* bar, unsigned x, unsigned& nloc, unsigned& nx) {
;     ...
;     for (;;) {
;         sum = 0u; cnt = 0u; mine = 0u;
; #pragma unroll
;         for (unsigned j = 0; j < 16; ++j) { const unsigned c = xb_ld(&bar[XB_XCNT(j)]); sum += c; cnt += (c > 0u) ? 1u : 0u; mine = (j == x) ? c : mine; }
; __device__ __forceinline__ void xcd_barrier(LAS unsigned char* lds_base, int wave) {
;     asm volatile("s_waitcnt vmcnt(0)" ::: "memory");
;     __syncthreads();
;     if (wave == 0 && lane_id() == 0) {
;         XcdBarrier b; b.bar = (unsigned*)(KWS + WS_BAR); b.x = xb_xcc_id(); b.st = (volatile LAS unsigned*)(lds_base + (LDS_BYTES - 16));
;         unsigned* bar = b.bar;
;         __builtin_amdgcn_s_waitcnt(0);
;         unsigned nloc = b.st[0], nx = b.st[1];
;         if (nloc == 0u) { xcd_barrier_complete(bar, b.x, nloc, nx); b.st[0] = nloc; b.st[1] = nx; }
.Lln_exit_ln1:
.LBB0_1020:
	s_waitcnt vmcnt(0)
	s_and_b64 vcc, exec, s[72:73]
	s_waitcnt lgkmcnt(0)
	s_barrier
	s_cbranch_vccnz .LBB0_1066
	v_mbcnt_lo_u32_b32 v0, -1, 0
	v_mbcnt_hi_u32_b32 v0, -1, v0
	s_nop 0
	v_cmp_eq_u32_e32 vcc, 0, v0
	s_and_saveexec_b64 s[62:63], vcc
	s_cbranch_execz .LBB0_1065
	s_add_i32 s4, 0, 0x257f0
	v_mov_b32_e32 v0, s4
	s_load_dwordx2 s[64:65], s[0:1], 0x90
	s_getreg_b32 s3, hwreg(HW_REG_XCC_ID, 0, 4)
	s_waitcnt vmcnt(0) expcnt(0) lgkmcnt(0)
	ds_read_b32 v2, v0
	s_add_i32 s4, 0, 0x257f4
	v_mov_b32_e32 v0, s4
	ds_read_b32 v0, v0
	s_and_b32 s3, s3, 15
	s_waitcnt lgkmcnt(1)
	v_cmp_ne_u32_e32 vcc, 0, v2
	s_cbranch_vccnz .LBB0_1036
	s_add_u32 s6, s64, 0x38060200
	s_addc_u32 s7, s65, 0
	s_add_u32 s10, s64, 0x38060400
	s_addc_u32 s11, s65, 0
	s_add_u32 s12, s64, 0x38060500
	s_addc_u32 s13, s65, 0
	s_add_u32 s14, s64, 0x38060600
	s_addc_u32 s15, s65, 0
	s_add_u32 s16, s64, 0x38060700
	s_addc_u32 s17, s65, 0
	s_add_u32 s18, s64, 0x38060800
	s_addc_u32 s19, s65, 0
	s_add_u32 s20, s64, 0x38060900
	s_addc_u32 s21, s65, 0
	s_add_u32 s22, s64, 0x38060a00
	s_addc_u32 s23, s65, 0
	s_add_u32 s24, s64, 0x38060b00
	s_addc_u32 s25, s65, 0
	s_add_u32 s26, s64, 0x38060c00
	s_addc_u32 s27, s65, 0
	s_add_u32 s28, s64, 0x38060d00
	s_addc_u32 s29, s65, 0
	s_add_u32 s30, s64, 0x38060e00
	s_addc_u32 s31, s65, 0
	s_add_u32 s34, s64, 0x38060f00
	s_addc_u32 s35, s65, 0
	s_add_u32 s36, s64, 0x38061000
	s_addc_u32 s37, s65, 0
	s_add_u32 s66, s64, 0x38061100
	s_addc_u32 s67, s65, 0
	s_add_u32 s72, s64, 0x38061200
	s_addc_u32 s73, s65, 0
	s_add_u32 s74, s64, 0x38061300
	s_addc_u32 s75, s65, 0
	s_mov_b32 s4, 1
	s_mov_b64 s[8:9], 0
	s_waitcnt lgkmcnt(0)
	v_mov_b64_e32 v[0:1], s[10:11]
	v_mov_b64_e32 v[2:3], s[12:13]
	v_mov_b64_e32 v[4:5], s[14:15]
	v_mov_b64_e32 v[6:7], s[16:17]
	v_mov_b64_e32 v[8:9], s[18:19]
	v_mov_b64_e32 v[10:11], s[20:21]
	v_mov_b64_e32 v[12:13], s[22:23]
	v_mov_b64_e32 v[14:15], s[24:25]
	v_mov_b64_e32 v[16:17], s[26:27]
	v_mov_b64_e32 v[18:19], s[28:29]
	v_mov_b64_e32 v[20:21], s[30:31]
	v_mov_b64_e32 v[22:23], s[34:35]
	v_mov_b64_e32 v[24:25], s[36:37]
	v_mov_b64_e32 v[26:27], s[66:67]
	v_mov_b64_e32 v[28:29], s[72:73]
	v_mov_b64_e32 v[30:31], s[74:75]
	s_branch .LBB0_1026

; __device__ __forceinline__ int lane_id() { int l; asm volatile("v_mbcnt_lo_u32_b32 %0, -1, 0\n\tv_mbcnt_hi_u32_b32 %0, -1, %0" : "=v"(l)); return l; }
; __device__ __forceinline__ void bf8_unpack(const u32x4 x, float (&f)[8]) { f[0] = bf_lo(x.x); f[1] = bf_hi(x.x); f[2] = bf_lo(x.y); f[3] = bf_hi(x.y); f[4] = bf_lo(x.z); f[5] = bf_hi(x.z); f[6] = bf_lo(x.w); f[7] = bf_hi(x.w); }
; template <bool FINAL>
; __device__ __forceinline__ void ln_phase(const bf16_t* pre, const float* gam, const float* bet, float* outf, bf16_t* outb, int wave) {
;     int lane_ = lane_id(); asm volatile("" : "+v"(lane_)); const int lane = lane_;
;     const int gw = blockIdx.x * 8 + wave, NGW = gridDim.x * 8;
;     for (int row = gw; row < NTOK; row += NGW) {
;         const u32x4* src = (const u32x4*)(pre + (size_t)row * DM) + lane;
;         float v[8][8]; float s = 0.f;
; #pragma unroll
;         for (int j = 0; j < 8; ++j) { const u32x4 x = src[64 * j]; bf8_unpack(x, v[j]);
;     ...
;         for (int j = 0; j < 8; ++j) {
;             const int c0 = 8 * (lane + 64 * j);
;             const f32x4 g0 = *(const f32x4*)(gam + c0), g1 = *(const f32x4*)(gam + c0 + 4), b0 = *(const f32x4*)(bet + c0), b1 = *(const f32x4*)(bet + c0 + 4);
.LBB0_1361:
	s_waitcnt lgkmcnt(0)
	s_barrier
	s_load_dwordx2 s[2:3], s[0:1], 0x78
	s_load_dwordx2 s[6:7], s[0:1], 0x80
	s_load_dwordx2 s[4:5], s[0:1], 0x88
	v_mbcnt_lo_u32_b32 v0, -1, 0
	v_mbcnt_hi_u32_b32 v0, -1, v0
	s_andn2_b64 vcc, exec, s[60:61]
	s_cbranch_vccnz .LBB0_1364
	v_mbcnt_hi_u32_b32 v4, -1, v192
	v_and_b32_e32 v2, 64, v4
	v_add_u32_e32 v5, 64, v2
	v_lshlrev_b32_e32 v2, 3, v0
	v_ashrrev_i32_e32 v3, 31, v2
	v_lshlrev_b64 v[16:17], 2, v[2:3]
	v_xor_b32_e32 v3, 1, v4
	v_cmp_lt_i32_e32 vcc, v3, v5
	s_ashr_i32 s39, s38, 31
	s_lshl_b64 s[0:1], s[38:39], 13
	v_cndmask_b32_e32 v3, v4, v3, vcc
	v_lshlrev_b32_e32 v95, 2, v3
	v_xor_b32_e32 v3, 2, v4
	v_cmp_lt_i32_e32 vcc, v3, v5
	s_add_u32 s0, s42, s0
	v_ashrrev_i32_e32 v1, 31, v0
	v_cndmask_b32_e32 v3, v4, v3, vcc
	v_lshlrev_b32_e32 v104, 2, v3
	v_xor_b32_e32 v3, 4, v4
	v_cmp_lt_i32_e32 vcc, v3, v5
	s_addc_u32 s1, s43, s1
	v_lshl_add_u64 v[0:1], v[0:1], 4, s[0:1]
	v_cndmask_b32_e32 v3, v4, v3, vcc
	v_lshlrev_b32_e32 v105, 2, v3
	v_xor_b32_e32 v3, 8, v4
	v_cmp_lt_i32_e32 vcc, v3, v5
	s_mov_b64 s[0:1], 0x24b01c00
	s_ashr_i32 s41, s40, 31
	v_cndmask_b32_e32 v3, v4, v3, vcc
	v_lshlrev_b32_e32 v106, 2, v3
	v_xor_b32_e32 v3, 16, v4
	v_cmp_lt_i32_e32 vcc, v3, v5
	s_waitcnt lgkmcnt(0)
	v_mbcnt_lo_u32_b32 v248, -1, 0
	v_mbcnt_hi_u32_b32 v248, -1, v248
	v_readlane_b32 s8, v250, 0
	s_nop 1
	v_lshl_add_u32 v216, s8, 6, v248
	v_lshlrev_b32_e32 v216, 5, v216
	v_lshlrev_b32_e32 v248, 5, v248
	global_load_dwordx4 v[220:223], v216, s[2:3]
	global_load_dwordx4 v[224:227], v216, s[2:3] offset:16
	global_load_dwordx4 v[228:231], v216, s[6:7]
	global_load_dwordx4 v[232:235], v216, s[6:7] offset:16
	s_waitcnt vmcnt(0)
	ds_write_b128 v216, v[220:223]
	ds_write_b128 v216, v[224:227] offset:16
	ds_write_b128 v216, v[228:231] offset:16384
	ds_write_b128 v216, v[232:235] offset:16400
	s_waitcnt lgkmcnt(0)
	s_barrier
	v_lshl_add_u64 v[18:19], s[2:3], 0, v[16:17]
	v_lshl_add_u64 v[58:59], v[0:1], 0, s[0:1]
	v_cndmask_b32_e32 v3, v4, v3, vcc
	v_lshlrev_b32_e32 v107, 2, v3
	v_xor_b32_e32 v3, 32, v4
	v_cmp_lt_i32_e32 vcc, v3, v5
	s_lshl_b64 s[0:1], s[38:39], 14
	v_lshl_add_u64 v[20:21], s[6:7], 0, v[16:17]
	v_cndmask_b32_e32 v3, v4, v3, vcc
	v_add_u32_e32 v4, 0x400, v2
	v_ashrrev_i32_e32 v5, 31, v4
	v_lshlrev_b64 v[22:23], 2, v[4:5]
	v_add_u32_e32 v4, 0x600, v2
	v_ashrrev_i32_e32 v5, 31, v4
	v_lshlrev_b64 v[28:29], 2, v[4:5]
	v_add_u32_e32 v4, 0x800, v2
	v_ashrrev_i32_e32 v5, 31, v4
	v_lshlrev_b64 v[34:35], 2, v[4:5]
	v_add_u32_e32 v4, 0xa00, v2
	v_ashrrev_i32_e32 v5, 31, v4
	v_lshlrev_b64 v[40:41], 2, v[4:5]
	v_add_u32_e32 v4, 0xc00, v2
	v_add_u32_e32 v2, 0xe00, v2
	v_lshlrev_b32_e32 v108, 2, v3
	v_ashrrev_i32_e32 v5, 31, v4
	v_ashrrev_i32_e32 v3, 31, v2
	v_lshlrev_b64 v[46:47], 2, v[4:5]
	v_lshlrev_b64 v[52:53], 2, v[2:3]
	v_lshl_add_u64 v[24:25], s[2:3], 0, v[22:23]
	v_lshl_add_u64 v[30:31], s[2:3], 0, v[28:29]
	v_lshl_add_u64 v[36:37], s[2:3], 0, v[34:35]
	v_lshl_add_u64 v[42:43], s[2:3], 0, v[40:41]
	v_lshl_add_u64 v[48:49], s[2:3], 0, v[46:47]
	v_lshl_add_u64 v[54:55], s[2:3], 0, v[52:53]
	s_lshl_b64 s[2:3], s[40:41], 13
	s_add_u32 s4, s4, s0
	v_lshl_add_u64 v[26:27], s[6:7], 0, v[22:23]
	v_lshl_add_u64 v[32:33], s[6:7], 0, v[28:29]
	v_lshl_add_u64 v[38:39], s[6:7], 0, v[34:35]
	v_lshl_add_u64 v[44:45], s[6:7], 0, v[40:41]
	v_lshl_add_u64 v[50:51], s[6:7], 0, v[46:47]
	v_lshl_add_u64 v[56:57], s[6:7], 0, v[52:53]
	s_addc_u32 s5, s5, s1
	s_lshl_b64 s[6:7], s[40:41], 14
	v_mov_b32_e32 v109, 0x3727c5ac
	s_mov_b32 s8, 0xf800000
	v_mov_b32_e32 v110, 0x260
	v_add_co_u32_e32 v248, vcc, 0xffffe400, v58
	s_nop 1
	v_addc_co_u32_e32 v249, vcc, -1, v59, vcc
	global_load_dwordx4 v[216:219], v[248:249], off
	global_load_dwordx4 v[220:223], v[248:249], off offset:1024
	global_load_dwordx4 v[224:227], v[248:249], off offset:2048
	global_load_dwordx4 v[228:231], v[248:249], off offset:3072
	v_add_co_u32_e32 v248, vcc, 0x1000, v248
	s_nop 1
	v_addc_co_u32_e32 v249, vcc, 0, v249, vcc
	global_load_dwordx4 v[232:235], v[248:249], off
	global_load_dwordx4 v[236:239], v[248:249], off offset:1024
	global_load_dwordx4 v[240:243], v[248:249], off offset:2048
	global_load_dwordx4 v[244:247], v[248:249], off offset:3072
	s_waitcnt vmcnt(0)
.LBB0_1363:
	v_lshl_add_u64 v[248:249], v[58:59], 0, s[2:3]
	v_add_co_u32_e32 v248, vcc, 0xffffe400, v248
	s_nop 1
	v_addc_co_u32_e32 v249, vcc, -1, v249, vcc
	global_load_dwordx4 v[18:21], v[248:249], off
	global_load_dwordx4 v[24:27], v[248:249], off offset:1024
	global_load_dwordx4 v[30:33], v[248:249], off offset:2048
	global_load_dwordx4 v[36:39], v[248:249], off offset:3072
	v_add_co_u32_e32 v248, vcc, 0x1000, v248
	s_nop 1
	v_addc_co_u32_e32 v249, vcc, 0, v249, vcc
	global_load_dwordx4 v[42:45], v[248:249], off
	global_load_dwordx4 v[48:51], v[248:249], off offset:1024
	global_load_dwordx4 v[54:57], v[248:249], off offset:2048
	global_load_dwordx4 v[252:255], v[248:249], off offset:3072
	v_add_co_u32_e32 v60, vcc, 0xffffe400, v58
	v_addc_co_u32_e32 v61, vcc, -1, v59, vcc
	v_add_co_u32_e32 v64, vcc, 0xffffe800, v58
	v_addc_co_u32_e32 v65, vcc, -1, v59, vcc
	v_add_co_u32_e32 v70, vcc, 0xffffec00, v58
	v_addc_co_u32_e32 v71, vcc, -1, v59, vcc
	v_add_co_u32_e32 v74, vcc, 0xfffff000, v58
	v_addc_co_u32_e32 v75, vcc, -1, v59, vcc
	v_add_co_u32_e32 v78, vcc, 0xfffff400, v58
	v_addc_co_u32_e32 v79, vcc, -1, v59, vcc
	v_add_co_u32_e32 v82, vcc, 0xfffff800, v58
	v_addc_co_u32_e32 v83, vcc, -1, v59, vcc
	v_add_co_u32_e32 v96, vcc, 0xfffffc00, v58
	v_addc_co_u32_e32 v97, vcc, -1, v59, vcc
	v_lshl_add_u64 v[68:69], s[4:5], 0, v[16:17]
	s_add_i32 s38, s38, s40
	v_lshl_add_u64 v[58:59], v[58:59], 0, s[2:3]
	ds_read_b128 v[4:7], v16 offset:0
	ds_read_b128 v[0:3], v16 offset:16
	ds_read_b128 v[12:15], v16 offset:16384
	ds_read_b128 v[8:11], v16 offset:16400
	ds_read_b128 v[200:203], v16 offset:18432
	ds_read_b128 v[204:207], v16 offset:2048
	ds_read_b128 v[208:211], v16 offset:2064
	ds_read_b128 v[212:215], v16 offset:18448
	s_waitcnt vmcnt(24) lgkmcnt(0)
; __device__ __forceinline__ void bf8_unpack(const u32x4 x, float (&f)[8]) { f[0] = bf_lo(x.x); f[1] = bf_hi(x.x); f[2] = bf_lo(x.y); f[3] = bf_hi(x.y); f[4] = bf_lo(x.z); f[5] = bf_hi(x.z); f[6] = bf_lo(x.w); f[7] = bf_hi(x.w); }
; template <bool FINAL>
; __device__ __forceinline__ void ln_phase(const bf16_t* pre, const float* gam, const float* bet, float* outf, bf16_t* outb, int wave) {
;     ...
;         for (int j = 0; j < 8; ++j) { const u32x4 x = src[64 * j]; bf8_unpack(x, v[j]);
; #pragma unroll
;             for (int e = 0; e < 8; ++e) s += v[j][e]; }
; #pragma unroll
;         for (int o = 1; o < 64; o <<= 1) s += __shfl_xor(s, o);
	v_lshlrev_b32_e32 v98, 16, v216
	v_and_b32_e32 v99, 0xffff0000, v216
	v_add_f32_e32 v94, 0, v98
	v_lshlrev_b32_e32 v60, 16, v217
	v_add_f32_e32 v94, v94, v99
	v_and_b32_e32 v61, 0xffff0000, v217
	v_add_f32_e32 v94, v94, v60
	v_lshlrev_b32_e32 v96, 16, v218
	v_add_f32_e32 v94, v94, v61
	v_and_b32_e32 v97, 0xffff0000, v218
	v_add_f32_e32 v94, v94, v96
	v_lshlrev_b32_e32 v62, 16, v219
	v_add_f32_e32 v94, v94, v97
	v_and_b32_e32 v63, 0xffff0000, v219
	v_lshlrev_b32_e32 v102, 16, v220
	v_and_b32_e32 v103, 0xffff0000, v220
	v_lshlrev_b32_e32 v64, 16, v221
	v_and_b32_e32 v65, 0xffff0000, v221
	v_lshlrev_b32_e32 v100, 16, v222
	v_and_b32_e32 v101, 0xffff0000, v222
	v_lshlrev_b32_e32 v66, 16, v223
	v_and_b32_e32 v67, 0xffff0000, v223
	v_lshlrev_b32_e32 v114, 16, v224
	v_and_b32_e32 v115, 0xffff0000, v224
	v_lshlrev_b32_e32 v70, 16, v225
	v_and_b32_e32 v71, 0xffff0000, v225
	v_lshlrev_b32_e32 v112, 16, v226
	v_lshlrev_b32_e32 v140, 16, v244
	v_and_b32_e32 v141, 0xffff0000, v244
	v_add_f32_e32 v86, v94, v62
	v_add_f32_e32 v86, v86, v63
	v_add_f32_e32 v86, v86, v102
	v_add_f32_e32 v86, v86, v103
	v_add_f32_e32 v86, v86, v64
	v_add_f32_e32 v86, v86, v65
	v_add_f32_e32 v86, v86, v100
	v_add_f32_e32 v86, v86, v101
	v_add_f32_e32 v86, v86, v66
	v_add_f32_e32 v86, v86, v67
	v_add_f32_e32 v86, v86, v114
	v_add_f32_e32 v86, v86, v115
	v_add_f32_e32 v86, v86, v70
	v_add_f32_e32 v86, v86, v71
	v_and_b32_e32 v113, 0xffff0000, v226
	v_add_f32_e32 v86, v86, v112
	v_lshlrev_b32_e32 v72, 16, v227
	v_add_f32_e32 v86, v86, v113
	v_and_b32_e32 v73, 0xffff0000, v227
	v_add_f32_e32 v86, v86, v72
	v_lshlrev_b32_e32 v118, 16, v228
	v_add_f32_e32 v86, v86, v73
	v_and_b32_e32 v119, 0xffff0000, v228
	v_add_f32_e32 v86, v86, v118
	v_lshlrev_b32_e32 v74, 16, v229
	v_add_f32_e32 v86, v86, v119
	v_and_b32_e32 v75, 0xffff0000, v229
	v_add_f32_e32 v86, v86, v74
	v_lshlrev_b32_e32 v116, 16, v230
	v_add_f32_e32 v86, v86, v75
	v_and_b32_e32 v117, 0xffff0000, v230
	v_add_f32_e32 v86, v86, v116
	v_lshlrev_b32_e32 v76, 16, v231
	v_add_f32_e32 v86, v86, v117
	v_and_b32_e32 v77, 0xffff0000, v231
	v_add_f32_e32 v86, v86, v76
	v_lshlrev_b32_e32 v122, 16, v232
	v_add_f32_e32 v86, v86, v77
	v_and_b32_e32 v123, 0xffff0000, v232
	v_add_f32_e32 v86, v86, v122
	v_lshlrev_b32_e32 v78, 16, v233
	v_add_f32_e32 v86, v86, v123
	v_and_b32_e32 v79, 0xffff0000, v233
	v_add_f32_e32 v86, v86, v78
	v_lshlrev_b32_e32 v120, 16, v234
	v_add_f32_e32 v86, v86, v79
	v_and_b32_e32 v121, 0xffff0000, v234
	v_add_f32_e32 v86, v86, v120
	v_lshlrev_b32_e32 v80, 16, v235
	v_add_f32_e32 v86, v86, v121
	v_and_b32_e32 v81, 0xffff0000, v235
	v_add_f32_e32 v86, v86, v80
	v_lshlrev_b32_e32 v126, 16, v236
	v_add_f32_e32 v86, v86, v81
	v_and_b32_e32 v127, 0xffff0000, v236
	v_add_f32_e32 v86, v86, v126
	v_lshlrev_b32_e32 v82, 16, v237
	v_add_f32_e32 v86, v86, v127
	v_and_b32_e32 v83, 0xffff0000, v237
	v_add_f32_e32 v86, v86, v82
	v_lshlrev_b32_e32 v124, 16, v238
	v_add_f32_e32 v86, v86, v83
	v_and_b32_e32 v125, 0xffff0000, v238
	v_add_f32_e32 v86, v86, v124
	v_lshlrev_b32_e32 v84, 16, v239
	v_add_f32_e32 v86, v86, v125
	v_and_b32_e32 v85, 0xffff0000, v239
	v_add_f32_e32 v86, v86, v84
	v_lshlrev_b32_e32 v134, 16, v240
	v_add_f32_e32 v86, v86, v85
	v_and_b32_e32 v135, 0xffff0000, v240
	v_add_f32_e32 v86, v86, v134
	v_lshlrev_b32_e32 v136, 16, v241
	v_add_f32_e32 v86, v86, v135
	v_and_b32_e32 v137, 0xffff0000, v241
	v_add_f32_e32 v86, v86, v136
	v_lshlrev_b32_e32 v130, 16, v242
	v_add_f32_e32 v86, v86, v137
	v_and_b32_e32 v131, 0xffff0000, v242
	v_add_f32_e32 v86, v86, v130
	v_lshlrev_b32_e32 v132, 16, v243
	v_add_f32_e32 v86, v86, v131
	v_and_b32_e32 v133, 0xffff0000, v243
	v_add_f32_e32 v86, v86, v132
	v_add_f32_e32 v86, v86, v133
	v_add_f32_e32 v86, v86, v140
	v_lshlrev_b32_e32 v142, 16, v245
	v_add_f32_e32 v86, v86, v141
	v_and_b32_e32 v143, 0xffff0000, v245
	v_add_f32_e32 v86, v86, v142
	v_lshlrev_b32_e32 v138, 16, v246
	v_add_f32_e32 v86, v86, v143
	v_and_b32_e32 v139, 0xffff0000, v246
	v_add_f32_e32 v86, v86, v138
	v_lshlrev_b32_e32 v129, 16, v247
	v_add_f32_e32 v86, v86, v139
	v_and_b32_e32 v128, 0xffff0000, v247
	v_add_f32_e32 v86, v86, v129
	v_add_f32_e32 v86, v86, v128
	ds_bpermute_b32 v87, v95, v86
	s_waitcnt lgkmcnt(0)
	v_add_f32_e32 v86, v86, v87
	ds_bpermute_b32 v87, v104, v86
	s_waitcnt lgkmcnt(0)
	v_add_f32_e32 v86, v86, v87
	ds_bpermute_b32 v87, v105, v86
	s_waitcnt lgkmcnt(0)
	v_add_f32_e32 v86, v86, v87
	ds_bpermute_b32 v87, v106, v86
	s_waitcnt lgkmcnt(0)
	v_add_f32_e32 v86, v86, v87
	ds_bpermute_b32 v87, v107, v86
	s_waitcnt lgkmcnt(0)
	v_add_f32_e32 v86, v86, v87
	ds_bpermute_b32 v87, v108, v86
	s_waitcnt lgkmcnt(0)
; template <bool FINAL>
; __device__ __forceinline__ void ln_phase(const bf16_t* pre, const float* gam, const float* bet, float* outf, bf16_t* outb, int wave) {
;     ...
;         const float mean = s * (1.0f / DM); float q = 0.f;
; #pragma unroll
;         for (int j = 0; j < 8; ++j)
; #pragma unroll
;             for (int e = 0; e < 8; ++e) { v[j][e] -= mean; q += v[j][e] * v[j][e]; }
; #pragma unroll
;         for (int o = 1; o < 64; o <<= 1) q += __shfl_xor(q, o);
	v_add_f32_e32 v86, v86, v87
	v_mul_f32_e32 v94, 0x39800000, v86
	v_pk_add_f32 v[144:145], v[98:99], v[94:95] op_sel_hi:[1, 0] neg_lo:[0, 1] neg_hi:[0, 1]
	v_pk_add_f32 v[146:147], v[60:61], v[94:95] op_sel_hi:[1, 0] neg_lo:[0, 1] neg_hi:[0, 1]
	v_pk_add_f32 v[98:99], v[116:117], v[94:95] op_sel_hi:[1, 0] neg_lo:[0, 1] neg_hi:[0, 1]
	v_pk_mul_f32 v[116:117], v[144:145], v[144:145]
	v_pk_add_f32 v[148:149], v[96:97], v[94:95] op_sel_hi:[1, 0] neg_lo:[0, 1] neg_hi:[0, 1]
	v_pk_add_f32 v[150:151], v[62:63], v[94:95] op_sel_hi:[1, 0] neg_lo:[0, 1] neg_hi:[0, 1]
	v_pk_add_f32 v[152:153], v[102:103], v[94:95] op_sel_hi:[1, 0] neg_lo:[0, 1] neg_hi:[0, 1]
	v_pk_add_f32 v[154:155], v[64:65], v[94:95] op_sel_hi:[1, 0] neg_lo:[0, 1] neg_hi:[0, 1]
	v_pk_add_f32 v[156:157], v[100:101], v[94:95] op_sel_hi:[1, 0] neg_lo:[0, 1] neg_hi:[0, 1]
	v_pk_add_f32 v[158:159], v[66:67], v[94:95] op_sel_hi:[1, 0] neg_lo:[0, 1] neg_hi:[0, 1]
	v_pk_add_f32 v[114:115], v[114:115], v[94:95] op_sel_hi:[1, 0] neg_lo:[0, 1] neg_hi:[0, 1]
	v_pk_add_f32 v[160:161], v[70:71], v[94:95] op_sel_hi:[1, 0] neg_lo:[0, 1] neg_hi:[0, 1]
	v_pk_add_f32 v[112:113], v[112:113], v[94:95] op_sel_hi:[1, 0] neg_lo:[0, 1] neg_hi:[0, 1]
	v_pk_add_f32 v[162:163], v[72:73], v[94:95] op_sel_hi:[1, 0] neg_lo:[0, 1] neg_hi:[0, 1]
	v_pk_add_f32 v[96:97], v[118:119], v[94:95] op_sel_hi:[1, 0] neg_lo:[0, 1] neg_hi:[0, 1]
	v_pk_add_f32 v[100:101], v[74:75], v[94:95] op_sel_hi:[1, 0] neg_lo:[0, 1] neg_hi:[0, 1]
	v_pk_add_f32 v[102:103], v[76:77], v[94:95] op_sel_hi:[1, 0] neg_lo:[0, 1] neg_hi:[0, 1]
	v_pk_add_f32 v[86:87], v[122:123], v[94:95] op_sel_hi:[1, 0] neg_lo:[0, 1] neg_hi:[0, 1]
	v_pk_add_f32 v[90:91], v[78:79], v[94:95] op_sel_hi:[1, 0] neg_lo:[0, 1] neg_hi:[0, 1]
	v_pk_add_f32 v[88:89], v[120:121], v[94:95] op_sel_hi:[1, 0] neg_lo:[0, 1] neg_hi:[0, 1]
	v_pk_add_f32 v[92:93], v[80:81], v[94:95] op_sel_hi:[1, 0] neg_lo:[0, 1] neg_hi:[0, 1]
	v_pk_add_f32 v[78:79], v[126:127], v[94:95] op_sel_hi:[1, 0] neg_lo:[0, 1] neg_hi:[0, 1]
	v_pk_add_f32 v[82:83], v[82:83], v[94:95] op_sel_hi:[1, 0] neg_lo:[0, 1] neg_hi:[0, 1]
	v_pk_add_f32 v[80:81], v[124:125], v[94:95] op_sel_hi:[1, 0] neg_lo:[0, 1] neg_hi:[0, 1]
	v_pk_add_f32 v[84:85], v[84:85], v[94:95] op_sel_hi:[1, 0] neg_lo:[0, 1] neg_hi:[0, 1]
	v_pk_add_f32 v[70:71], v[134:135], v[94:95] op_sel_hi:[1, 0] neg_lo:[0, 1] neg_hi:[0, 1]
	v_pk_add_f32 v[74:75], v[136:137], v[94:95] op_sel_hi:[1, 0] neg_lo:[0, 1] neg_hi:[0, 1]
	v_pk_add_f32 v[72:73], v[130:131], v[94:95] op_sel_hi:[1, 0] neg_lo:[0, 1] neg_hi:[0, 1]
	v_pk_add_f32 v[76:77], v[132:133], v[94:95] op_sel_hi:[1, 0] neg_lo:[0, 1] neg_hi:[0, 1]
	v_pk_add_f32 v[60:61], v[140:141], v[94:95] op_sel_hi:[1, 0] neg_lo:[0, 1] neg_hi:[0, 1]
	v_pk_add_f32 v[64:65], v[142:143], v[94:95] op_sel_hi:[1, 0] neg_lo:[0, 1] neg_hi:[0, 1]
	v_pk_add_f32 v[62:63], v[138:139], v[94:95] op_sel_hi:[1, 0] neg_lo:[0, 1] neg_hi:[0, 1]
	v_pk_add_f32 v[66:67], v[128:129], v[94:95] op_sel_hi:[1, 0] neg_lo:[0, 1] neg_hi:[0, 1]
	v_pk_mul_f32 v[118:119], v[146:147], v[146:147]
	v_add_f32_e32 v94, v116, v117
	v_add_f32_e32 v94, v118, v94
	v_pk_mul_f32 v[120:121], v[148:149], v[148:149]
	v_add_f32_e32 v94, v119, v94
	v_add_f32_e32 v94, v120, v94
	v_pk_mul_f32 v[122:123], v[150:151], v[150:151]
	v_add_f32_e32 v94, v121, v94
	v_add_f32_e32 v94, v122, v94
	v_pk_mul_f32 v[124:125], v[152:153], v[152:153]
	v_add_f32_e32 v94, v123, v94
	v_add_f32_e32 v94, v124, v94
	v_pk_mul_f32 v[126:127], v[154:155], v[154:155]
	v_add_f32_e32 v94, v125, v94
	v_add_f32_e32 v94, v126, v94
	v_pk_mul_f32 v[128:129], v[156:157], v[156:157]
	v_add_f32_e32 v94, v127, v94
	v_add_f32_e32 v94, v128, v94
	v_pk_mul_f32 v[130:131], v[158:159], v[158:159]
	v_add_f32_e32 v94, v129, v94
	v_add_f32_e32 v94, v130, v94
	v_pk_mul_f32 v[132:133], v[114:115], v[114:115]
	v_add_f32_e32 v94, v131, v94
	v_add_f32_e32 v94, v132, v94
	v_pk_mul_f32 v[134:135], v[160:161], v[160:161]
	v_add_f32_e32 v94, v133, v94
	v_add_f32_e32 v94, v134, v94
	v_pk_mul_f32 v[136:137], v[112:113], v[112:113]
	v_add_f32_e32 v94, v135, v94
	v_add_f32_e32 v94, v136, v94
	v_pk_mul_f32 v[138:139], v[162:163], v[162:163]
	v_add_f32_e32 v94, v137, v94
	v_add_f32_e32 v94, v138, v94
	v_pk_mul_f32 v[140:141], v[96:97], v[96:97]
	v_add_f32_e32 v94, v139, v94
	v_add_f32_e32 v94, v140, v94
	v_pk_mul_f32 v[142:143], v[100:101], v[100:101]
	v_add_f32_e32 v94, v141, v94
	v_add_f32_e32 v94, v142, v94
	v_pk_mul_f32 v[164:165], v[98:99], v[98:99]
	v_add_f32_e32 v94, v143, v94
	v_add_f32_e32 v94, v164, v94
	v_pk_mul_f32 v[166:167], v[102:103], v[102:103]
	v_add_f32_e32 v94, v165, v94
	v_add_f32_e32 v94, v166, v94
	v_pk_mul_f32 v[168:169], v[86:87], v[86:87]
	v_add_f32_e32 v94, v167, v94
	v_add_f32_e32 v94, v168, v94
	v_pk_mul_f32 v[170:171], v[90:91], v[90:91]
	v_add_f32_e32 v94, v169, v94
	v_add_f32_e32 v94, v170, v94
	v_pk_mul_f32 v[172:173], v[88:89], v[88:89]
	v_add_f32_e32 v94, v171, v94
	v_add_f32_e32 v94, v172, v94
	v_pk_mul_f32 v[174:175], v[92:93], v[92:93]
	v_add_f32_e32 v94, v173, v94
	v_add_f32_e32 v94, v174, v94
	v_pk_mul_f32 v[176:177], v[78:79], v[78:79]
	v_add_f32_e32 v94, v175, v94
	v_add_f32_e32 v94, v176, v94
	v_pk_mul_f32 v[178:179], v[82:83], v[82:83]
	v_add_f32_e32 v94, v177, v94
	v_add_f32_e32 v94, v178, v94
	v_pk_mul_f32 v[180:181], v[80:81], v[80:81]
	v_add_f32_e32 v94, v179, v94
	v_add_f32_e32 v94, v180, v94
	v_pk_mul_f32 v[182:183], v[84:85], v[84:85]
	v_add_f32_e32 v94, v181, v94
	v_add_f32_e32 v94, v182, v94
	v_pk_mul_f32 v[184:185], v[70:71], v[70:71]
	v_add_f32_e32 v94, v183, v94
	v_add_f32_e32 v94, v184, v94
	v_pk_mul_f32 v[186:187], v[74:75], v[74:75]
	v_add_f32_e32 v94, v185, v94
	v_add_f32_e32 v94, v186, v94
	v_pk_mul_f32 v[188:189], v[72:73], v[72:73]
	v_add_f32_e32 v94, v187, v94
	v_add_f32_e32 v94, v188, v94
	v_pk_mul_f32 v[190:191], v[76:77], v[76:77]
	v_add_f32_e32 v94, v189, v94
	v_add_f32_e32 v94, v190, v94
	v_pk_mul_f32 v[192:193], v[60:61], v[60:61]
	v_add_f32_e32 v94, v191, v94
	v_add_f32_e32 v94, v192, v94
	v_pk_mul_f32 v[194:195], v[64:65], v[64:65]
	v_add_f32_e32 v94, v193, v94
	v_add_f32_e32 v94, v194, v94
	v_pk_mul_f32 v[196:197], v[62:63], v[62:63]
	v_add_f32_e32 v94, v195, v94
	v_add_f32_e32 v94, v196, v94
	v_pk_mul_f32 v[198:199], v[66:67], v[66:67]
	v_add_f32_e32 v94, v197, v94
	v_add_f32_e32 v94, v199, v94
	v_add_f32_e32 v94, v198, v94
	ds_bpermute_b32 v111, v95, v94
	s_waitcnt lgkmcnt(0)
; __device__ __forceinline__ unsigned pk2(float lo, float hi) { const bf16x2_t v = __builtin_convertvector((f32x2_t){lo, hi}, bf16x2_t); return __builtin_bit_cast(unsigned, v); }
; template <bool FINAL>
; __device__ __forceinline__ void ln_phase(const bf16_t* pre, const float* gam, const float* bet, float* outf, bf16_t* outb, int wave) {
;     ...
;         for (int o = 1; o < 64; o <<= 1) q += __shfl_xor(q, o);
;         const float rstd = 1.0f / sqrtf(q * (1.0f / DM) + LN_EPS);
; #pragma unroll
;         for (int j = 0; j < 8; ++j) {
;             const int c0 = 8 * (lane + 64 * j);
;             const f32x4 g0 = *(const f32x4*)(gam + c0), g1 = *(const f32x4*)(gam + c0 + 4), b0 = *(const f32x4*)(bet + c0), b1 = *(const f32x4*)(bet + c0 + 4);
;             const f32x4 y0 = (f32x4){v[j][0], v[j][1], v[j][2], v[j][3]} * rstd * g0 + b0, y1 = (f32x4){v[j][4], v[j][5], v[j][6], v[j][7]} * rstd * g1 + b1;
;             if (FINAL) { float* o = outf + (size_t)row * DM + c0; *(f32x4*)o = y0; *(f32x4*)(o + 4) = y1; }
;             else { u32x4 w; w.x = pk2(y0.x, y0.y); w.y = pk2(y0.z, y0.w); w.z = pk2(y1.x, y1.y); w.w = pk2(y1.z, y1.w); *(u32x4*)(outb + (size_t)row * DM + c0) = w; }
	v_add_f32_e32 v94, v94, v111
	ds_bpermute_b32 v111, v104, v94
	s_waitcnt lgkmcnt(0)
	v_add_f32_e32 v94, v94, v111
	ds_bpermute_b32 v111, v105, v94
	s_waitcnt lgkmcnt(0)
	v_add_f32_e32 v94, v94, v111
	ds_bpermute_b32 v111, v106, v94
	s_waitcnt lgkmcnt(0)
	v_add_f32_e32 v94, v94, v111
	ds_bpermute_b32 v111, v107, v94
	s_waitcnt lgkmcnt(0)
	v_add_f32_e32 v94, v94, v111
	ds_bpermute_b32 v111, v108, v94
	s_waitcnt lgkmcnt(0)
	v_add_f32_e32 v94, v94, v111
	v_fmamk_f32 v94, v94, 0x39800000, v109
	v_mul_f32_e32 v111, 0x4f800000, v94
	v_cmp_gt_f32_e32 vcc, s8, v94
	s_nop 1
	v_cndmask_b32_e32 v94, v94, v111, vcc
	v_sqrt_f32_e32 v111, v94
	s_nop 0
	v_add_u32_e32 v116, -1, v111
	v_add_u32_e32 v117, 1, v111
	v_fma_f32 v118, -v116, v111, v94
	v_fma_f32 v119, -v117, v111, v94
	v_cmp_ge_f32_e64 s[0:1], 0, v118
	s_nop 1
	v_cndmask_b32_e64 v111, v111, v116, s[0:1]
	v_cmp_lt_f32_e64 s[0:1], 0, v119
	s_nop 1
	v_cndmask_b32_e64 v111, v111, v117, s[0:1]
	v_mul_f32_e32 v116, 0x37800000, v111
	v_cndmask_b32_e32 v111, v111, v116, vcc
	v_cmp_class_f32_e32 vcc, v94, v110
	s_nop 1
	v_cndmask_b32_e32 v94, v111, v94, vcc
	v_div_scale_f32 v111, s[0:1], v94, v94, 1.0
	v_rcp_f32_e32 v117, v111
	v_div_scale_f32 v116, vcc, 1.0, v94, 1.0
	v_fma_f32 v118, -v111, v117, 1.0
	v_fmac_f32_e32 v117, v118, v117
	v_mul_f32_e32 v118, v116, v117
	v_fma_f32 v119, -v111, v118, v116
	v_fmac_f32_e32 v118, v119, v117
	v_fma_f32 v111, -v111, v118, v116
	v_div_fmas_f32 v111, v111, v117, v118
	v_div_fixup_f32 v94, v111, v94, 1.0
	v_pk_mul_f32 v[116:117], v[144:145], v[94:95] op_sel_hi:[1, 0]
	v_pk_mul_f32 v[118:119], v[146:147], v[94:95] op_sel_hi:[1, 0]
	v_pk_mul_f32 v[120:121], v[148:149], v[94:95] op_sel_hi:[1, 0]
	v_pk_mul_f32 v[122:123], v[150:151], v[94:95] op_sel_hi:[1, 0]
	v_pk_fma_f32 v[6:7], v[6:7], v[118:119], v[14:15]
	v_pk_fma_f32 v[4:5], v[4:5], v[116:117], v[12:13]
	v_pk_fma_f32 v[2:3], v[2:3], v[122:123], v[10:11]
	v_pk_fma_f32 v[0:1], v[0:1], v[120:121], v[8:9]
	global_store_dwordx4 v[68:69], v[4:7], off
	global_store_dwordx4 v[68:69], v[0:3], off offset:16
	ds_read_b128 v[0:3], v16 offset:20480
	ds_read_b128 v[4:7], v16 offset:4096
	ds_read_b128 v[8:11], v16 offset:4112
	ds_read_b128 v[12:15], v16 offset:20496
	v_pk_mul_f32 v[116:117], v[154:155], v[94:95] op_sel_hi:[1, 0]
	v_pk_mul_f32 v[118:119], v[152:153], v[94:95] op_sel_hi:[1, 0]
	v_pk_mul_f32 v[120:121], v[158:159], v[94:95] op_sel_hi:[1, 0]
	v_pk_mul_f32 v[122:123], v[156:157], v[94:95] op_sel_hi:[1, 0]
	v_pk_mul_f32 v[114:115], v[114:115], v[94:95] op_sel_hi:[1, 0]
	v_pk_mul_f32 v[112:113], v[112:113], v[94:95] op_sel_hi:[1, 0]
	v_pk_mul_f32 v[100:101], v[100:101], v[94:95] op_sel_hi:[1, 0]
	v_pk_mul_f32 v[96:97], v[96:97], v[94:95] op_sel_hi:[1, 0]
	v_pk_mul_f32 v[102:103], v[102:103], v[94:95] op_sel_hi:[1, 0]
	v_pk_mul_f32 v[98:99], v[98:99], v[94:95] op_sel_hi:[1, 0]
	v_pk_mul_f32 v[90:91], v[90:91], v[94:95] op_sel_hi:[1, 0]
	v_pk_mul_f32 v[86:87], v[86:87], v[94:95] op_sel_hi:[1, 0]
	v_pk_mul_f32 v[92:93], v[92:93], v[94:95] op_sel_hi:[1, 0]
	v_pk_mul_f32 v[88:89], v[88:89], v[94:95] op_sel_hi:[1, 0]
	v_pk_mul_f32 v[82:83], v[82:83], v[94:95] op_sel_hi:[1, 0]
	v_pk_mul_f32 v[78:79], v[78:79], v[94:95] op_sel_hi:[1, 0]
	v_pk_mul_f32 v[84:85], v[84:85], v[94:95] op_sel_hi:[1, 0]
	v_pk_mul_f32 v[80:81], v[80:81], v[94:95] op_sel_hi:[1, 0]
	v_pk_mul_f32 v[74:75], v[74:75], v[94:95] op_sel_hi:[1, 0]
	v_pk_mul_f32 v[70:71], v[70:71], v[94:95] op_sel_hi:[1, 0]
	v_pk_mul_f32 v[76:77], v[76:77], v[94:95] op_sel_hi:[1, 0]
	v_pk_mul_f32 v[72:73], v[72:73], v[94:95] op_sel_hi:[1, 0]
	v_pk_mul_f32 v[64:65], v[64:65], v[94:95] op_sel_hi:[1, 0]
	v_pk_mul_f32 v[60:61], v[60:61], v[94:95] op_sel_hi:[1, 0]
	v_pk_mul_f32 v[66:67], v[66:67], v[94:95] op_sel:[1, 0] op_sel_hi:[0, 0]
	v_pk_mul_f32 v[62:63], v[62:63], v[94:95] op_sel_hi:[1, 0]
	v_pk_fma_f32 v[200:201], v[204:205], v[118:119], v[200:201]
	v_pk_fma_f32 v[202:203], v[206:207], v[116:117], v[202:203]
	v_pk_fma_f32 v[204:205], v[208:209], v[122:123], v[212:213]
	v_pk_fma_f32 v[206:207], v[210:211], v[120:121], v[214:215]
	global_store_dwordx4 v[68:69], v[200:203], off offset:2048
	global_store_dwordx4 v[68:69], v[204:207], off offset:2064
	ds_read_b128 v[200:203], v16 offset:22528
	ds_read_b128 v[204:207], v16 offset:6144
	ds_read_b128 v[208:211], v16 offset:6160
	ds_read_b128 v[212:215], v16 offset:22544
	v_pk_mul_f32 v[116:117], v[160:161], v[94:95] op_sel_hi:[1, 0]
	v_lshl_add_u64 v[68:69], s[4:5], 0, v[22:23]
	v_pk_mul_f32 v[118:119], v[162:163], v[94:95] op_sel_hi:[1, 0]
	s_waitcnt lgkmcnt(4)
	v_pk_fma_f32 v[0:1], v[4:5], v[114:115], v[0:1]
	v_pk_fma_f32 v[2:3], v[6:7], v[116:117], v[2:3]
	v_pk_fma_f32 v[4:5], v[8:9], v[112:113], v[12:13]
	v_pk_fma_f32 v[6:7], v[10:11], v[118:119], v[14:15]
	global_store_dwordx4 v[68:69], v[0:3], off
	global_store_dwordx4 v[68:69], v[4:7], off offset:16
	ds_read_b128 v[0:3], v16 offset:24576
	ds_read_b128 v[4:7], v16 offset:8192
	ds_read_b128 v[8:11], v16 offset:8208
	ds_read_b128 v[12:15], v16 offset:24592
	v_lshl_add_u64 v[68:69], s[4:5], 0, v[28:29]
	s_waitcnt lgkmcnt(4)
	v_pk_fma_f32 v[200:201], v[204:205], v[96:97], v[200:201]
	v_pk_fma_f32 v[202:203], v[206:207], v[100:101], v[202:203]
	v_pk_fma_f32 v[204:205], v[208:209], v[98:99], v[212:213]
	v_pk_fma_f32 v[206:207], v[210:211], v[102:103], v[214:215]
	global_store_dwordx4 v[68:69], v[200:203], off
	global_store_dwordx4 v[68:69], v[204:207], off offset:16
	ds_read_b128 v[200:203], v16 offset:26624
	ds_read_b128 v[204:207], v16 offset:10240
	ds_read_b128 v[208:211], v16 offset:10256
	ds_read_b128 v[212:215], v16 offset:26640
	v_lshl_add_u64 v[68:69], s[4:5], 0, v[34:35]
	s_waitcnt lgkmcnt(4)
; __device__ __forceinline__ unsigned pk2(float lo, float hi) { const bf16x2_t v = __builtin_convertvector((f32x2_t){lo, hi}, bf16x2_t); return __builtin_bit_cast(unsigned, v); }
; __device__ __forceinline__ void bf8_unpack(const u32x4 x, float (&f)[8]) { f[0] = bf_lo(x.x); f[1] = bf_hi(x.x); f[2] = bf_lo(x.y); f[3] = bf_hi(x.y); f[4] = bf_lo(x.z); f[5] = bf_hi(x.z); f[6] = bf_lo(x.w); f[7] = bf_hi(x.w); }
; template <bool FINAL>
; __device__ __forceinline__ void ln_phase(const bf16_t* pre, const float* gam, const float* bet, float* outf, bf16_t* outb, int wave) {
;     ...
;     for (int row = gw; row < NTOK; row += NGW) {
;         const u32x4* src = (const u32x4*)(pre + (size_t)row * DM) + lane;
;         float v[8][8]; float s = 0.f;
; #pragma unroll
;         for (int j = 0; j < 8; ++j) { const u32x4 x = src[64 * j]; bf8_unpack(x, v[j]);
; #pragma unroll
;             for (int e = 0; e < 8; ++e) s += v[j][e]; }
;     ...
;         for (int j = 0; j < 8; ++j) {
;             const int c0 = 8 * (lane + 64 * j);
;             const f32x4 g0 = *(const f32x4*)(gam + c0), g1 = *(const f32x4*)(gam + c0 + 4), b0 = *(const f32x4*)(bet + c0), b1 = *(const f32x4*)(bet + c0 + 4);
;             const f32x4 y0 = (f32x4){v[j][0], v[j][1], v[j][2], v[j][3]} * rstd * g0 + b0, y1 = (f32x4){v[j][4], v[j][5], v[j][6], v[j][7]} * rstd * g1 + b1;
;             if (FINAL) { float* o = outf + (size_t)row * DM + c0; *(f32x4*)o = y0; *(f32x4*)(o + 4) = y1; }
;             else { u32x4 w; w.x = pk2(y0.x, y0.y); w.y = pk2(y0.z, y0.w); w.z = pk2(y1.x, y1.y); w.w = pk2(y1.z, y1.w); *(u32x4*)(outb + (size_t)row * DM + c0) = w; }
;         }
	v_pk_fma_f32 v[0:1], v[4:5], v[86:87], v[0:1]
	v_pk_fma_f32 v[2:3], v[6:7], v[90:91], v[2:3]
	v_pk_fma_f32 v[4:5], v[8:9], v[88:89], v[12:13]
	v_pk_fma_f32 v[6:7], v[10:11], v[92:93], v[14:15]
	global_store_dwordx4 v[68:69], v[0:3], off
	global_store_dwordx4 v[68:69], v[4:7], off offset:16
	ds_read_b128 v[0:3], v16 offset:28672
	ds_read_b128 v[4:7], v16 offset:12288
	ds_read_b128 v[8:11], v16 offset:12304
	ds_read_b128 v[12:15], v16 offset:28688
	v_lshl_add_u64 v[68:69], s[4:5], 0, v[40:41]
	s_waitcnt lgkmcnt(4)
	v_pk_fma_f32 v[200:201], v[204:205], v[78:79], v[200:201]
	v_pk_fma_f32 v[202:203], v[206:207], v[82:83], v[202:203]
	v_pk_fma_f32 v[204:205], v[208:209], v[80:81], v[212:213]
	v_pk_fma_f32 v[206:207], v[210:211], v[84:85], v[214:215]
	global_store_dwordx4 v[68:69], v[200:203], off
	global_store_dwordx4 v[68:69], v[204:207], off offset:16
	ds_read_b128 v[200:203], v16 offset:30720
	ds_read_b128 v[204:207], v16 offset:14336
	ds_read_b128 v[208:211], v16 offset:14352
	ds_read_b128 v[212:215], v16 offset:30736
	v_lshl_add_u64 v[68:69], s[4:5], 0, v[46:47]
	s_waitcnt lgkmcnt(4)
	v_pk_fma_f32 v[0:1], v[4:5], v[70:71], v[0:1]
	v_pk_fma_f32 v[2:3], v[6:7], v[74:75], v[2:3]
	v_pk_fma_f32 v[4:5], v[8:9], v[72:73], v[12:13]
	v_pk_fma_f32 v[6:7], v[10:11], v[76:77], v[14:15]
	global_store_dwordx4 v[68:69], v[0:3], off
	global_store_dwordx4 v[68:69], v[4:7], off offset:16
	v_lshl_add_u64 v[68:69], s[4:5], 0, v[52:53]
	s_add_u32 s4, s4, s6
	s_addc_u32 s5, s5, s7
	s_cmpk_lt_i32 s38, 0x2100
	s_waitcnt lgkmcnt(0)
	v_pk_fma_f32 v[200:201], v[204:205], v[60:61], v[200:201]
	v_pk_fma_f32 v[202:203], v[206:207], v[64:65], v[202:203]
	v_pk_fma_f32 v[204:205], v[208:209], v[62:63], v[212:213]
	v_pk_fma_f32 v[206:207], v[210:211], v[66:67], v[214:215]
	global_store_dwordx4 v[68:69], v[200:203], off
	global_store_dwordx4 v[68:69], v[204:207], off offset:16
	s_cbranch_scc0 .Lln_exit_ln2
	v_lshl_add_u64 v[248:249], v[58:59], 0, s[2:3]
	v_add_co_u32_e32 v248, vcc, 0xffffe400, v248
	s_nop 1
	v_addc_co_u32_e32 v249, vcc, -1, v249, vcc
	global_load_dwordx4 v[216:219], v[248:249], off
	global_load_dwordx4 v[220:223], v[248:249], off offset:1024
	global_load_dwordx4 v[224:227], v[248:249], off offset:2048
	global_load_dwordx4 v[228:231], v[248:249], off offset:3072
	v_add_co_u32_e32 v248, vcc, 0x1000, v248
	s_nop 1
	v_addc_co_u32_e32 v249, vcc, 0, v249, vcc
	global_load_dwordx4 v[232:235], v[248:249], off
	global_load_dwordx4 v[236:239], v[248:249], off offset:1024
	global_load_dwordx4 v[240:243], v[248:249], off offset:2048
	global_load_dwordx4 v[244:247], v[248:249], off offset:3072
	v_add_co_u32_e32 v60, vcc, 0xffffe400, v58
	v_addc_co_u32_e32 v61, vcc, -1, v59, vcc
	v_add_co_u32_e32 v64, vcc, 0xffffe800, v58
	v_addc_co_u32_e32 v65, vcc, -1, v59, vcc
	v_add_co_u32_e32 v70, vcc, 0xffffec00, v58
	v_addc_co_u32_e32 v71, vcc, -1, v59, vcc
	v_add_co_u32_e32 v74, vcc, 0xfffff000, v58
	v_addc_co_u32_e32 v75, vcc, -1, v59, vcc
	v_add_co_u32_e32 v78, vcc, 0xfffff400, v58
	v_addc_co_u32_e32 v79, vcc, -1, v59, vcc
	v_add_co_u32_e32 v82, vcc, 0xfffff800, v58
	v_addc_co_u32_e32 v83, vcc, -1, v59, vcc
	v_add_co_u32_e32 v96, vcc, 0xfffffc00, v58
	v_addc_co_u32_e32 v97, vcc, -1, v59, vcc
	v_lshl_add_u64 v[68:69], s[4:5], 0, v[16:17]
	s_add_i32 s38, s38, s40
	v_lshl_add_u64 v[58:59], v[58:59], 0, s[2:3]
	ds_read_b128 v[4:7], v16 offset:0
	ds_read_b128 v[0:3], v16 offset:16
	ds_read_b128 v[12:15], v16 offset:16384
	ds_read_b128 v[8:11], v16 offset:16400
	ds_read_b128 v[200:203], v16 offset:18432
	ds_read_b128 v[204:207], v16 offset:2048
	ds_read_b128 v[208:211], v16 offset:2064
	ds_read_b128 v[212:215], v16 offset:18448
	s_waitcnt vmcnt(24) lgkmcnt(0)
	v_lshlrev_b32_e32 v98, 16, v18
	v_and_b32_e32 v99, 0xffff0000, v18
	v_add_f32_e32 v94, 0, v98
	v_lshlrev_b32_e32 v60, 16, v19
	v_add_f32_e32 v94, v94, v99
	v_and_b32_e32 v61, 0xffff0000, v19
	v_add_f32_e32 v94, v94, v60
	v_lshlrev_b32_e32 v96, 16, v20
	v_add_f32_e32 v94, v94, v61
	v_and_b32_e32 v97, 0xffff0000, v20
	v_add_f32_e32 v94, v94, v96
	v_lshlrev_b32_e32 v62, 16, v21
	v_add_f32_e32 v94, v94, v97
	v_and_b32_e32 v63, 0xffff0000, v21
	v_lshlrev_b32_e32 v102, 16, v24
	v_and_b32_e32 v103, 0xffff0000, v24
	v_lshlrev_b32_e32 v64, 16, v25
	v_and_b32_e32 v65, 0xffff0000, v25
	v_lshlrev_b32_e32 v100, 16, v26
	v_and_b32_e32 v101, 0xffff0000, v26
	v_lshlrev_b32_e32 v66, 16, v27
	v_and_b32_e32 v67, 0xffff0000, v27
	v_lshlrev_b32_e32 v114, 16, v30
	v_and_b32_e32 v115, 0xffff0000, v30
	v_lshlrev_b32_e32 v70, 16, v31
	v_and_b32_e32 v71, 0xffff0000, v31
	v_lshlrev_b32_e32 v112, 16, v32
	v_lshlrev_b32_e32 v140, 16, v252
	v_and_b32_e32 v141, 0xffff0000, v252
	v_add_f32_e32 v86, v94, v62
	v_add_f32_e32 v86, v86, v63
	v_add_f32_e32 v86, v86, v102
	v_add_f32_e32 v86, v86, v103
	v_add_f32_e32 v86, v86, v64
	v_add_f32_e32 v86, v86, v65
	v_add_f32_e32 v86, v86, v100
	v_add_f32_e32 v86, v86, v101
	v_add_f32_e32 v86, v86, v66
	v_add_f32_e32 v86, v86, v67
	v_add_f32_e32 v86, v86, v114
	v_add_f32_e32 v86, v86, v115
	v_add_f32_e32 v86, v86, v70
	v_add_f32_e32 v86, v86, v71
	v_and_b32_e32 v113, 0xffff0000, v32
	v_add_f32_e32 v86, v86, v112
	v_lshlrev_b32_e32 v72, 16, v33
	v_add_f32_e32 v86, v86, v113
	v_and_b32_e32 v73, 0xffff0000, v33
	v_add_f32_e32 v86, v86, v72
	v_lshlrev_b32_e32 v118, 16, v36
	v_add_f32_e32 v86, v86, v73
	v_and_b32_e32 v119, 0xffff0000, v36
	v_add_f32_e32 v86, v86, v118
	v_lshlrev_b32_e32 v74, 16, v37
	v_add_f32_e32 v86, v86, v119
	v_and_b32_e32 v75, 0xffff0000, v37
	v_add_f32_e32 v86, v86, v74
	v_lshlrev_b32_e32 v116, 16, v38
	v_add_f32_e32 v86, v86, v75
	v_and_b32_e32 v117, 0xffff0000, v38
	v_add_f32_e32 v86, v86, v116
; __device__ __forceinline__ void bf8_unpack(const u32x4 x, float (&f)[8]) { f[0] = bf_lo(x.x); f[1] = bf_hi(x.x); f[2] = bf_lo(x.y); f[3] = bf_hi(x.y); f[4] = bf_lo(x.z); f[5] = bf_hi(x.z); f[6] = bf_lo(x.w); f[7] = bf_hi(x.w); }
; template <bool FINAL>
; __device__ __forceinline__ void ln_phase(const bf16_t* pre, const float* gam, const float* bet, float* outf, bf16_t* outb, int wave) {
;     ...
;         for (int j = 0; j < 8; ++j) { const u32x4 x = src[64 * j]; bf8_unpack(x, v[j]);
; #pragma unroll
;             for (int e = 0; e < 8; ++e) s += v[j][e]; }
; #pragma unroll
;         for (int o = 1; o < 64; o <<= 1) s += __shfl_xor(s, o);
;         const float mean = s * (1.0f / DM); float q = 0.f;
; #pragma unroll
;         for (int j = 0; j < 8; ++j)
; #pragma unroll
;             for (int e = 0; e < 8; ++e) { v[j][e] -= mean; q += v[j][e] * v[j][e]; }
	v_lshlrev_b32_e32 v76, 16, v39
	v_add_f32_e32 v86, v86, v117
	v_and_b32_e32 v77, 0xffff0000, v39
	v_add_f32_e32 v86, v86, v76
	v_lshlrev_b32_e32 v122, 16, v42
	v_add_f32_e32 v86, v86, v77
	v_and_b32_e32 v123, 0xffff0000, v42
	v_add_f32_e32 v86, v86, v122
	v_lshlrev_b32_e32 v78, 16, v43
	v_add_f32_e32 v86, v86, v123
	v_and_b32_e32 v79, 0xffff0000, v43
	v_add_f32_e32 v86, v86, v78
	v_lshlrev_b32_e32 v120, 16, v44
	v_add_f32_e32 v86, v86, v79
	v_and_b32_e32 v121, 0xffff0000, v44
	v_add_f32_e32 v86, v86, v120
	v_lshlrev_b32_e32 v80, 16, v45
	v_add_f32_e32 v86, v86, v121
	v_and_b32_e32 v81, 0xffff0000, v45
	v_add_f32_e32 v86, v86, v80
	v_lshlrev_b32_e32 v126, 16, v48
	v_add_f32_e32 v86, v86, v81
	v_and_b32_e32 v127, 0xffff0000, v48
	v_add_f32_e32 v86, v86, v126
	v_lshlrev_b32_e32 v82, 16, v49
	v_add_f32_e32 v86, v86, v127
	v_and_b32_e32 v83, 0xffff0000, v49
	v_add_f32_e32 v86, v86, v82
	v_lshlrev_b32_e32 v124, 16, v50
	v_add_f32_e32 v86, v86, v83
	v_and_b32_e32 v125, 0xffff0000, v50
	v_add_f32_e32 v86, v86, v124
	v_lshlrev_b32_e32 v84, 16, v51
	v_add_f32_e32 v86, v86, v125
	v_and_b32_e32 v85, 0xffff0000, v51
	v_add_f32_e32 v86, v86, v84
	v_lshlrev_b32_e32 v134, 16, v54
	v_add_f32_e32 v86, v86, v85
	v_and_b32_e32 v135, 0xffff0000, v54
	v_add_f32_e32 v86, v86, v134
	v_lshlrev_b32_e32 v136, 16, v55
	v_add_f32_e32 v86, v86, v135
	v_and_b32_e32 v137, 0xffff0000, v55
	v_add_f32_e32 v86, v86, v136
	v_lshlrev_b32_e32 v130, 16, v56
	v_add_f32_e32 v86, v86, v137
	v_and_b32_e32 v131, 0xffff0000, v56
	v_add_f32_e32 v86, v86, v130
	v_lshlrev_b32_e32 v132, 16, v57
	v_add_f32_e32 v86, v86, v131
	v_and_b32_e32 v133, 0xffff0000, v57
	v_add_f32_e32 v86, v86, v132
	v_add_f32_e32 v86, v86, v133
	v_add_f32_e32 v86, v86, v140
	v_lshlrev_b32_e32 v142, 16, v253
	v_add_f32_e32 v86, v86, v141
	v_and_b32_e32 v143, 0xffff0000, v253
	v_add_f32_e32 v86, v86, v142
	v_lshlrev_b32_e32 v138, 16, v254
	v_add_f32_e32 v86, v86, v143
	v_and_b32_e32 v139, 0xffff0000, v254
	v_add_f32_e32 v86, v86, v138
	v_lshlrev_b32_e32 v129, 16, v255
	v_add_f32_e32 v86, v86, v139
	v_and_b32_e32 v128, 0xffff0000, v255
	v_add_f32_e32 v86, v86, v129
	v_add_f32_e32 v86, v86, v128
	ds_bpermute_b32 v87, v95, v86
	s_waitcnt lgkmcnt(0)
	v_add_f32_e32 v86, v86, v87
	ds_bpermute_b32 v87, v104, v86
	s_waitcnt lgkmcnt(0)
	v_add_f32_e32 v86, v86, v87
	ds_bpermute_b32 v87, v105, v86
	s_waitcnt lgkmcnt(0)
	v_add_f32_e32 v86, v86, v87
	ds_bpermute_b32 v87, v106, v86
	s_waitcnt lgkmcnt(0)
	v_add_f32_e32 v86, v86, v87
	ds_bpermute_b32 v87, v107, v86
	s_waitcnt lgkmcnt(0)
	v_add_f32_e32 v86, v86, v87
	ds_bpermute_b32 v87, v108, v86
	s_waitcnt lgkmcnt(0)
	v_add_f32_e32 v86, v86, v87
	v_mul_f32_e32 v94, 0x39800000, v86
	v_pk_add_f32 v[144:145], v[98:99], v[94:95] op_sel_hi:[1, 0] neg_lo:[0, 1] neg_hi:[0, 1]
	v_pk_add_f32 v[146:147], v[60:61], v[94:95] op_sel_hi:[1, 0] neg_lo:[0, 1] neg_hi:[0, 1]
	v_pk_add_f32 v[98:99], v[116:117], v[94:95] op_sel_hi:[1, 0] neg_lo:[0, 1] neg_hi:[0, 1]
	v_pk_mul_f32 v[116:117], v[144:145], v[144:145]
	v_pk_add_f32 v[148:149], v[96:97], v[94:95] op_sel_hi:[1, 0] neg_lo:[0, 1] neg_hi:[0, 1]
	v_pk_add_f32 v[150:151], v[62:63], v[94:95] op_sel_hi:[1, 0] neg_lo:[0, 1] neg_hi:[0, 1]
	v_pk_add_f32 v[152:153], v[102:103], v[94:95] op_sel_hi:[1, 0] neg_lo:[0, 1] neg_hi:[0, 1]
	v_pk_add_f32 v[154:155], v[64:65], v[94:95] op_sel_hi:[1, 0] neg_lo:[0, 1] neg_hi:[0, 1]
	v_pk_add_f32 v[156:157], v[100:101], v[94:95] op_sel_hi:[1, 0] neg_lo:[0, 1] neg_hi:[0, 1]
	v_pk_add_f32 v[158:159], v[66:67], v[94:95] op_sel_hi:[1, 0] neg_lo:[0, 1] neg_hi:[0, 1]
	v_pk_add_f32 v[114:115], v[114:115], v[94:95] op_sel_hi:[1, 0] neg_lo:[0, 1] neg_hi:[0, 1]
	v_pk_add_f32 v[160:161], v[70:71], v[94:95] op_sel_hi:[1, 0] neg_lo:[0, 1] neg_hi:[0, 1]
	v_pk_add_f32 v[112:113], v[112:113], v[94:95] op_sel_hi:[1, 0] neg_lo:[0, 1] neg_hi:[0, 1]
	v_pk_add_f32 v[162:163], v[72:73], v[94:95] op_sel_hi:[1, 0] neg_lo:[0, 1] neg_hi:[0, 1]
	v_pk_add_f32 v[96:97], v[118:119], v[94:95] op_sel_hi:[1, 0] neg_lo:[0, 1] neg_hi:[0, 1]
	v_pk_add_f32 v[100:101], v[74:75], v[94:95] op_sel_hi:[1, 0] neg_lo:[0, 1] neg_hi:[0, 1]
	v_pk_add_f32 v[102:103], v[76:77], v[94:95] op_sel_hi:[1, 0] neg_lo:[0, 1] neg_hi:[0, 1]
	v_pk_add_f32 v[86:87], v[122:123], v[94:95] op_sel_hi:[1, 0] neg_lo:[0, 1] neg_hi:[0, 1]
	v_pk_add_f32 v[90:91], v[78:79], v[94:95] op_sel_hi:[1, 0] neg_lo:[0, 1] neg_hi:[0, 1]
	v_pk_add_f32 v[88:89], v[120:121], v[94:95] op_sel_hi:[1, 0] neg_lo:[0, 1] neg_hi:[0, 1]
	v_pk_add_f32 v[92:93], v[80:81], v[94:95] op_sel_hi:[1, 0] neg_lo:[0, 1] neg_hi:[0, 1]
	v_pk_add_f32 v[78:79], v[126:127], v[94:95] op_sel_hi:[1, 0] neg_lo:[0, 1] neg_hi:[0, 1]
	v_pk_add_f32 v[82:83], v[82:83], v[94:95] op_sel_hi:[1, 0] neg_lo:[0, 1] neg_hi:[0, 1]
	v_pk_add_f32 v[80:81], v[124:125], v[94:95] op_sel_hi:[1, 0] neg_lo:[0, 1] neg_hi:[0, 1]
	v_pk_add_f32 v[84:85], v[84:85], v[94:95] op_sel_hi:[1, 0] neg_lo:[0, 1] neg_hi:[0, 1]
	v_pk_add_f32 v[70:71], v[134:135], v[94:95] op_sel_hi:[1, 0] neg_lo:[0, 1] neg_hi:[0, 1]
	v_pk_add_f32 v[74:75], v[136:137], v[94:95] op_sel_hi:[1, 0] neg_lo:[0, 1] neg_hi:[0, 1]
	v_pk_add_f32 v[72:73], v[130:131], v[94:95] op_sel_hi:[1, 0] neg_lo:[0, 1] neg_hi:[0, 1]
	v_pk_add_f32 v[76:77], v[132:133], v[94:95] op_sel_hi:[1, 0] neg_lo:[0, 1] neg_hi:[0, 1]
	v_pk_add_f32 v[60:61], v[140:141], v[94:95] op_sel_hi:[1, 0] neg_lo:[0, 1] neg_hi:[0, 1]
	v_pk_add_f32 v[64:65], v[142:143], v[94:95] op_sel_hi:[1, 0] neg_lo:[0, 1] neg_hi:[0, 1]
	v_pk_add_f32 v[62:63], v[138:139], v[94:95] op_sel_hi:[1, 0] neg_lo:[0, 1] neg_hi:[0, 1]
	v_pk_add_f32 v[66:67], v[128:129], v[94:95] op_sel_hi:[1, 0] neg_lo:[0, 1] neg_hi:[0, 1]
; __device__ __forceinline__ unsigned pk2(float lo, float hi) { const bf16x2_t v = __builtin_convertvector((f32x2_t){lo, hi}, bf16x2_t); return __builtin_bit_cast(unsigned, v); }
; template <bool FINAL>
; __device__ __forceinline__ void ln_phase(const bf16_t* pre, const float* gam, const float* bet, float* outf, bf16_t* outb, int wave) {
;     ...
;         for (int o = 1; o < 64; o <<= 1) s += __shfl_xor(s, o);
;         const float mean = s * (1.0f / DM); float q = 0.f;
; #pragma unroll
;         for (int j = 0; j < 8; ++j)
; #pragma unroll
;             for (int e = 0; e < 8; ++e) { v[j][e] -= mean; q += v[j][e] * v[j][e]; }
; #pragma unroll
;         for (int o = 1; o < 64; o <<= 1) q += __shfl_xor(q, o);
;         const float rstd = 1.0f / sqrtf(q * (1.0f / DM) + LN_EPS);
; #pragma unroll
;         for (int j = 0; j < 8; ++j) {
;             const int c0 = 8 * (lane + 64 * j);
;             const f32x4 g0 = *(const f32x4*)(gam + c0), g1 = *(const f32x4*)(gam + c0 + 4), b0 = *(const f32x4*)(bet + c0), b1 = *(const f32x4*)(bet + c0 + 4);
;             const f32x4 y0 = (f32x4){v[j][0], v[j][1], v[j][2], v[j][3]} * rstd * g0 + b0, y1 = (f32x4){v[j][4], v[j][5], v[j][6], v[j][7]} * rstd * g1 + b1;
;             if (FINAL) { float* o = outf + (size_t)row * DM + c0; *(f32x4*)o = y0; *(f32x4*)(o + 4) = y1; }
;             else { u32x4 w; w.x = pk2(y0.x, y0.y); w.y = pk2(y0.z, y0.w); w.z = pk2(y1.x, y1.y); w.w = pk2(y1.z, y1.w); *(u32x4*)(outb + (size_t)row * DM + c0) = w; }
	v_pk_mul_f32 v[118:119], v[146:147], v[146:147]
	v_add_f32_e32 v94, v116, v117
	v_add_f32_e32 v94, v118, v94
	v_pk_mul_f32 v[120:121], v[148:149], v[148:149]
	v_add_f32_e32 v94, v119, v94
	v_add_f32_e32 v94, v120, v94
	v_pk_mul_f32 v[122:123], v[150:151], v[150:151]
	v_add_f32_e32 v94, v121, v94
	v_add_f32_e32 v94, v122, v94
	v_pk_mul_f32 v[124:125], v[152:153], v[152:153]
	v_add_f32_e32 v94, v123, v94
	v_add_f32_e32 v94, v124, v94
	v_pk_mul_f32 v[126:127], v[154:155], v[154:155]
	v_add_f32_e32 v94, v125, v94
	v_add_f32_e32 v94, v126, v94
	v_pk_mul_f32 v[128:129], v[156:157], v[156:157]
	v_add_f32_e32 v94, v127, v94
	v_add_f32_e32 v94, v128, v94
	v_pk_mul_f32 v[130:131], v[158:159], v[158:159]
	v_add_f32_e32 v94, v129, v94
	v_add_f32_e32 v94, v130, v94
	v_pk_mul_f32 v[132:133], v[114:115], v[114:115]
	v_add_f32_e32 v94, v131, v94
	v_add_f32_e32 v94, v132, v94
	v_pk_mul_f32 v[134:135], v[160:161], v[160:161]
	v_add_f32_e32 v94, v133, v94
	v_add_f32_e32 v94, v134, v94
	v_pk_mul_f32 v[136:137], v[112:113], v[112:113]
	v_add_f32_e32 v94, v135, v94
	v_add_f32_e32 v94, v136, v94
	v_pk_mul_f32 v[138:139], v[162:163], v[162:163]
	v_add_f32_e32 v94, v137, v94
	v_add_f32_e32 v94, v138, v94
	v_pk_mul_f32 v[140:141], v[96:97], v[96:97]
	v_add_f32_e32 v94, v139, v94
	v_add_f32_e32 v94, v140, v94
	v_pk_mul_f32 v[142:143], v[100:101], v[100:101]
	v_add_f32_e32 v94, v141, v94
	v_add_f32_e32 v94, v142, v94
	v_pk_mul_f32 v[164:165], v[98:99], v[98:99]
	v_add_f32_e32 v94, v143, v94
	v_add_f32_e32 v94, v164, v94
	v_pk_mul_f32 v[166:167], v[102:103], v[102:103]
	v_add_f32_e32 v94, v165, v94
	v_add_f32_e32 v94, v166, v94
	v_pk_mul_f32 v[168:169], v[86:87], v[86:87]
	v_add_f32_e32 v94, v167, v94
	v_add_f32_e32 v94, v168, v94
	v_pk_mul_f32 v[170:171], v[90:91], v[90:91]
	v_add_f32_e32 v94, v169, v94
	v_add_f32_e32 v94, v170, v94
	v_pk_mul_f32 v[172:173], v[88:89], v[88:89]
	v_add_f32_e32 v94, v171, v94
	v_add_f32_e32 v94, v172, v94
	v_pk_mul_f32 v[174:175], v[92:93], v[92:93]
	v_add_f32_e32 v94, v173, v94
	v_add_f32_e32 v94, v174, v94
	v_pk_mul_f32 v[176:177], v[78:79], v[78:79]
	v_add_f32_e32 v94, v175, v94
	v_add_f32_e32 v94, v176, v94
	v_pk_mul_f32 v[178:179], v[82:83], v[82:83]
	v_add_f32_e32 v94, v177, v94
	v_add_f32_e32 v94, v178, v94
	v_pk_mul_f32 v[180:181], v[80:81], v[80:81]
	v_add_f32_e32 v94, v179, v94
	v_add_f32_e32 v94, v180, v94
	v_pk_mul_f32 v[182:183], v[84:85], v[84:85]
	v_add_f32_e32 v94, v181, v94
	v_add_f32_e32 v94, v182, v94
	v_pk_mul_f32 v[184:185], v[70:71], v[70:71]
	v_add_f32_e32 v94, v183, v94
	v_add_f32_e32 v94, v184, v94
	v_pk_mul_f32 v[186:187], v[74:75], v[74:75]
	v_add_f32_e32 v94, v185, v94
	v_add_f32_e32 v94, v186, v94
	v_pk_mul_f32 v[188:189], v[72:73], v[72:73]
	v_add_f32_e32 v94, v187, v94
	v_add_f32_e32 v94, v188, v94
	v_pk_mul_f32 v[190:191], v[76:77], v[76:77]
	v_add_f32_e32 v94, v189, v94
	v_add_f32_e32 v94, v190, v94
	v_pk_mul_f32 v[192:193], v[60:61], v[60:61]
	v_add_f32_e32 v94, v191, v94
	v_add_f32_e32 v94, v192, v94
	v_pk_mul_f32 v[194:195], v[64:65], v[64:65]
	v_add_f32_e32 v94, v193, v94
	v_add_f32_e32 v94, v194, v94
	v_pk_mul_f32 v[196:197], v[62:63], v[62:63]
	v_add_f32_e32 v94, v195, v94
	v_add_f32_e32 v94, v196, v94
	v_pk_mul_f32 v[198:199], v[66:67], v[66:67]
	v_add_f32_e32 v94, v197, v94
	v_add_f32_e32 v94, v199, v94
	v_add_f32_e32 v94, v198, v94
	ds_bpermute_b32 v111, v95, v94
	s_waitcnt lgkmcnt(0)
	v_add_f32_e32 v94, v94, v111
	ds_bpermute_b32 v111, v104, v94
	s_waitcnt lgkmcnt(0)
	v_add_f32_e32 v94, v94, v111
	ds_bpermute_b32 v111, v105, v94
	s_waitcnt lgkmcnt(0)
	v_add_f32_e32 v94, v94, v111
	ds_bpermute_b32 v111, v106, v94
	s_waitcnt lgkmcnt(0)
	v_add_f32_e32 v94, v94, v111
	ds_bpermute_b32 v111, v107, v94
	s_waitcnt lgkmcnt(0)
	v_add_f32_e32 v94, v94, v111
	ds_bpermute_b32 v111, v108, v94
	s_waitcnt lgkmcnt(0)
	v_add_f32_e32 v94, v94, v111
	v_fmamk_f32 v94, v94, 0x39800000, v109
	v_mul_f32_e32 v111, 0x4f800000, v94
	v_cmp_gt_f32_e32 vcc, s8, v94
	s_nop 1
	v_cndmask_b32_e32 v94, v94, v111, vcc
	v_sqrt_f32_e32 v111, v94
	s_nop 0
	v_add_u32_e32 v116, -1, v111
	v_add_u32_e32 v117, 1, v111
	v_fma_f32 v118, -v116, v111, v94
	v_fma_f32 v119, -v117, v111, v94
	v_cmp_ge_f32_e64 s[0:1], 0, v118
	s_nop 1
	v_cndmask_b32_e64 v111, v111, v116, s[0:1]
	v_cmp_lt_f32_e64 s[0:1], 0, v119
	s_nop 1
	v_cndmask_b32_e64 v111, v111, v117, s[0:1]
	v_mul_f32_e32 v116, 0x37800000, v111
	v_cndmask_b32_e32 v111, v111, v116, vcc
	v_cmp_class_f32_e32 vcc, v94, v110
	s_nop 1
	v_cndmask_b32_e32 v94, v111, v94, vcc
	v_div_scale_f32 v111, s[0:1], v94, v94, 1.0
	v_rcp_f32_e32 v117, v111
	v_div_scale_f32 v116, vcc, 1.0, v94, 1.0
	v_fma_f32 v118, -v111, v117, 1.0
	v_fmac_f32_e32 v117, v118, v117
	v_mul_f32_e32 v118, v116, v117
	v_fma_f32 v119, -v111, v118, v116
	v_fmac_f32_e32 v118, v119, v117
	v_fma_f32 v111, -v111, v118, v116
	v_div_fmas_f32 v111, v111, v117, v118
	v_div_fixup_f32 v94, v111, v94, 1.0
	v_pk_mul_f32 v[116:117], v[144:145], v[94:95] op_sel_hi:[1, 0]
	v_pk_mul_f32 v[118:119], v[146:147], v[94:95] op_sel_hi:[1, 0]
	v_pk_mul_f32 v[120:121], v[148:149], v[94:95] op_sel_hi:[1, 0]
	v_pk_mul_f32 v[122:123], v[150:151], v[94:95] op_sel_hi:[1, 0]
	v_pk_fma_f32 v[6:7], v[6:7], v[118:119], v[14:15]
	v_pk_fma_f32 v[4:5], v[4:5], v[116:117], v[12:13]
	v_pk_fma_f32 v[2:3], v[2:3], v[122:123], v[10:11]
	v_pk_fma_f32 v[0:1], v[0:1], v[120:121], v[8:9]
	global_store_dwordx4 v[68:69], v[4:7], off
	global_store_dwordx4 v[68:69], v[0:3], off offset:16
	ds_read_b128 v[0:3], v16 offset:20480
; __device__ __forceinline__ unsigned pk2(float lo, float hi) { const bf16x2_t v = __builtin_convertvector((f32x2_t){lo, hi}, bf16x2_t); return __builtin_bit_cast(unsigned, v); }
; template <bool FINAL>
; __device__ __forceinline__ void ln_phase(const bf16_t* pre, const float* gam, const float* bet, float* outf, bf16_t* outb, int wave) {
;     ...
; #pragma unroll
;         for (int j = 0; j < 8; ++j) {
;             const int c0 = 8 * (lane + 64 * j);
;             const f32x4 g0 = *(const f32x4*)(gam + c0), g1 = *(const f32x4*)(gam + c0 + 4), b0 = *(const f32x4*)(bet + c0), b1 = *(const f32x4*)(bet + c0 + 4);
;             const f32x4 y0 = (f32x4){v[j][0], v[j][1], v[j][2], v[j][3]} * rstd * g0 + b0, y1 = (f32x4){v[j][4], v[j][5], v[j][6], v[j][7]} * rstd * g1 + b1;
;             if (FINAL) { float* o = outf + (size_t)row * DM + c0; *(f32x4*)o = y0; *(f32x4*)(o + 4) = y1; }
;             else { u32x4 w; w.x = pk2(y0.x, y0.y); w.y = pk2(y0.z, y0.w); w.z = pk2(y1.x, y1.y); w.w = pk2(y1.z, y1.w); *(u32x4*)(outb + (size_t)row * DM + c0) = w; }
;         }
;     }
	ds_read_b128 v[4:7], v16 offset:4096
	ds_read_b128 v[8:11], v16 offset:4112
	ds_read_b128 v[12:15], v16 offset:20496
	v_pk_mul_f32 v[116:117], v[154:155], v[94:95] op_sel_hi:[1, 0]
	v_pk_mul_f32 v[118:119], v[152:153], v[94:95] op_sel_hi:[1, 0]
	v_pk_mul_f32 v[120:121], v[158:159], v[94:95] op_sel_hi:[1, 0]
	v_pk_mul_f32 v[122:123], v[156:157], v[94:95] op_sel_hi:[1, 0]
	v_pk_mul_f32 v[114:115], v[114:115], v[94:95] op_sel_hi:[1, 0]
	v_pk_mul_f32 v[112:113], v[112:113], v[94:95] op_sel_hi:[1, 0]
	v_pk_mul_f32 v[100:101], v[100:101], v[94:95] op_sel_hi:[1, 0]
	v_pk_mul_f32 v[96:97], v[96:97], v[94:95] op_sel_hi:[1, 0]
	v_pk_mul_f32 v[102:103], v[102:103], v[94:95] op_sel_hi:[1, 0]
	v_pk_mul_f32 v[98:99], v[98:99], v[94:95] op_sel_hi:[1, 0]
	v_pk_mul_f32 v[90:91], v[90:91], v[94:95] op_sel_hi:[1, 0]
	v_pk_mul_f32 v[86:87], v[86:87], v[94:95] op_sel_hi:[1, 0]
	v_pk_mul_f32 v[92:93], v[92:93], v[94:95] op_sel_hi:[1, 0]
	v_pk_mul_f32 v[88:89], v[88:89], v[94:95] op_sel_hi:[1, 0]
	v_pk_mul_f32 v[82:83], v[82:83], v[94:95] op_sel_hi:[1, 0]
	v_pk_mul_f32 v[78:79], v[78:79], v[94:95] op_sel_hi:[1, 0]
	v_pk_mul_f32 v[84:85], v[84:85], v[94:95] op_sel_hi:[1, 0]
	v_pk_mul_f32 v[80:81], v[80:81], v[94:95] op_sel_hi:[1, 0]
	v_pk_mul_f32 v[74:75], v[74:75], v[94:95] op_sel_hi:[1, 0]
	v_pk_mul_f32 v[70:71], v[70:71], v[94:95] op_sel_hi:[1, 0]
	v_pk_mul_f32 v[76:77], v[76:77], v[94:95] op_sel_hi:[1, 0]
	v_pk_mul_f32 v[72:73], v[72:73], v[94:95] op_sel_hi:[1, 0]
	v_pk_mul_f32 v[64:65], v[64:65], v[94:95] op_sel_hi:[1, 0]
	v_pk_mul_f32 v[60:61], v[60:61], v[94:95] op_sel_hi:[1, 0]
	v_pk_mul_f32 v[66:67], v[66:67], v[94:95] op_sel:[1, 0] op_sel_hi:[0, 0]
	v_pk_mul_f32 v[62:63], v[62:63], v[94:95] op_sel_hi:[1, 0]
	v_pk_fma_f32 v[200:201], v[204:205], v[118:119], v[200:201]
	v_pk_fma_f32 v[202:203], v[206:207], v[116:117], v[202:203]
	v_pk_fma_f32 v[204:205], v[208:209], v[122:123], v[212:213]
	v_pk_fma_f32 v[206:207], v[210:211], v[120:121], v[214:215]
	global_store_dwordx4 v[68:69], v[200:203], off offset:2048
	global_store_dwordx4 v[68:69], v[204:207], off offset:2064
	ds_read_b128 v[200:203], v16 offset:22528
	ds_read_b128 v[204:207], v16 offset:6144
	ds_read_b128 v[208:211], v16 offset:6160
	ds_read_b128 v[212:215], v16 offset:22544
	v_pk_mul_f32 v[116:117], v[160:161], v[94:95] op_sel_hi:[1, 0]
	v_lshl_add_u64 v[68:69], s[4:5], 0, v[22:23]
	v_pk_mul_f32 v[118:119], v[162:163], v[94:95] op_sel_hi:[1, 0]
	s_waitcnt lgkmcnt(4)
	v_pk_fma_f32 v[0:1], v[4:5], v[114:115], v[0:1]
	v_pk_fma_f32 v[2:3], v[6:7], v[116:117], v[2:3]
	v_pk_fma_f32 v[4:5], v[8:9], v[112:113], v[12:13]
	v_pk_fma_f32 v[6:7], v[10:11], v[118:119], v[14:15]
	global_store_dwordx4 v[68:69], v[0:3], off
	global_store_dwordx4 v[68:69], v[4:7], off offset:16
	ds_read_b128 v[0:3], v16 offset:24576
	ds_read_b128 v[4:7], v16 offset:8192
	ds_read_b128 v[8:11], v16 offset:8208
	ds_read_b128 v[12:15], v16 offset:24592
	v_lshl_add_u64 v[68:69], s[4:5], 0, v[28:29]
	s_waitcnt lgkmcnt(4)
	v_pk_fma_f32 v[200:201], v[204:205], v[96:97], v[200:201]
	v_pk_fma_f32 v[202:203], v[206:207], v[100:101], v[202:203]
	v_pk_fma_f32 v[204:205], v[208:209], v[98:99], v[212:213]
	v_pk_fma_f32 v[206:207], v[210:211], v[102:103], v[214:215]
	global_store_dwordx4 v[68:69], v[200:203], off
	global_store_dwordx4 v[68:69], v[204:207], off offset:16
	ds_read_b128 v[200:203], v16 offset:26624
	ds_read_b128 v[204:207], v16 offset:10240
	ds_read_b128 v[208:211], v16 offset:10256
	ds_read_b128 v[212:215], v16 offset:26640
	v_lshl_add_u64 v[68:69], s[4:5], 0, v[34:35]
	s_waitcnt lgkmcnt(4)
	v_pk_fma_f32 v[0:1], v[4:5], v[86:87], v[0:1]
	v_pk_fma_f32 v[2:3], v[6:7], v[90:91], v[2:3]
	v_pk_fma_f32 v[4:5], v[8:9], v[88:89], v[12:13]
	v_pk_fma_f32 v[6:7], v[10:11], v[92:93], v[14:15]
	global_store_dwordx4 v[68:69], v[0:3], off
	global_store_dwordx4 v[68:69], v[4:7], off offset:16
	ds_read_b128 v[0:3], v16 offset:28672
	ds_read_b128 v[4:7], v16 offset:12288
	ds_read_b128 v[8:11], v16 offset:12304
	ds_read_b128 v[12:15], v16 offset:28688
	v_lshl_add_u64 v[68:69], s[4:5], 0, v[40:41]
	s_waitcnt lgkmcnt(4)
	v_pk_fma_f32 v[200:201], v[204:205], v[78:79], v[200:201]
	v_pk_fma_f32 v[202:203], v[206:207], v[82:83], v[202:203]
	v_pk_fma_f32 v[204:205], v[208:209], v[80:81], v[212:213]
	v_pk_fma_f32 v[206:207], v[210:211], v[84:85], v[214:215]
	global_store_dwordx4 v[68:69], v[200:203], off
	global_store_dwordx4 v[68:69], v[204:207], off offset:16
	ds_read_b128 v[200:203], v16 offset:30720
	ds_read_b128 v[204:207], v16 offset:14336
	ds_read_b128 v[208:211], v16 offset:14352
	ds_read_b128 v[212:215], v16 offset:30736
	v_lshl_add_u64 v[68:69], s[4:5], 0, v[46:47]
	s_waitcnt lgkmcnt(4)
	v_pk_fma_f32 v[0:1], v[4:5], v[70:71], v[0:1]
	v_pk_fma_f32 v[2:3], v[6:7], v[74:75], v[2:3]
	v_pk_fma_f32 v[4:5], v[8:9], v[72:73], v[12:13]
	v_pk_fma_f32 v[6:7], v[10:11], v[76:77], v[14:15]
	global_store_dwordx4 v[68:69], v[0:3], off
	global_store_dwordx4 v[68:69], v[4:7], off offset:16
	v_lshl_add_u64 v[68:69], s[4:5], 0, v[52:53]
	s_add_u32 s4, s4, s6
	s_addc_u32 s5, s5, s7
	s_cmpk_lt_i32 s38, 0x2100
	s_waitcnt lgkmcnt(0)
	v_pk_fma_f32 v[200:201], v[204:205], v[60:61], v[200:201]
	v_pk_fma_f32 v[202:203], v[206:207], v[64:65], v[202:203]
	v_pk_fma_f32 v[204:205], v[208:209], v[62:63], v[212:213]
	v_pk_fma_f32 v[206:207], v[210:211], v[66:67], v[214:215]
	global_store_dwordx4 v[68:69], v[200:203], off
	global_store_dwordx4 v[68:69], v[204:207], off offset:16
	s_cbranch_scc1 .LBB0_1363
.Lln_exit_ln2:
.LBB0_1364:
	s_endpgm

; __global__ void __launch_bounds__(512, 2) mega_fwd(Params p) {
	.amdhsa_kernel _Z8mega_fwd6Params
		.amdhsa_group_segment_fixed_size 0
		.amdhsa_private_segment_fixed_size 0
		.amdhsa_kernarg_size 408
		.amdhsa_user_sgpr_count 2
		.amdhsa_user_sgpr_dispatch_ptr 0
		.amdhsa_user_sgpr_queue_ptr 0
		.amdhsa_user_sgpr_kernarg_segment_ptr 1
		.amdhsa_user_sgpr_dispatch_id 0
		.amdhsa_user_sgpr_kernarg_preload_length 0
		.amdhsa_user_sgpr_kernarg_preload_offset 0
		.amdhsa_user_sgpr_private_segment_size 0
		.amdhsa_uses_dynamic_stack 0
		.amdhsa_enable_private_segment 0
		.amdhsa_system_sgpr_workgroup_id_x 1
		.amdhsa_system_sgpr_workgroup_id_y 0
		.amdhsa_system_sgpr_workgroup_id_z 0
		.amdhsa_system_sgpr_workgroup_info 0
		.amdhsa_system_vgpr_workitem_id 2
		.amdhsa_next_free_vgpr 256
		.amdhsa_next_free_sgpr 98
		.amdhsa_accum_offset 256
		.amdhsa_reserve_vcc 1
		.amdhsa_float_round_mode_32 0
		.amdhsa_float_round_mode_16_64 0
		.amdhsa_float_denorm_mode_32 3
		.amdhsa_float_denorm_mode_16_64 3
		.amdhsa_dx10_clamp 1
		.amdhsa_ieee_mode 1
		.amdhsa_fp16_overflow 0
		.amdhsa_tg_split 0
		.amdhsa_exception_fp_ieee_invalid_op 0
		.amdhsa_exception_fp_denorm_src 0
		.amdhsa_exception_fp_ieee_div_zero 0
		.amdhsa_exception_fp_ieee_overflow 0
		.amdhsa_exception_fp_ieee_underflow 0
		.amdhsa_exception_fp_ieee_inexact 0
		.amdhsa_exception_int_div_zero 0
	.end_amdhsa_kernel

; __global__ void __launch_bounds__(512, 2) mega_fwd(Params p) {
amdhsa.kernels:
  - .agpr_count:     0
    .args:
      - .offset:         0
        .size:           152
        .value_kind:     by_value
      - .offset:         152
        .size:           4
        .value_kind:     hidden_block_count_x
      - .offset:         156
        .size:           4
        .value_kind:     hidden_block_count_y
      - .offset:         160
        .size:           4
        .value_kind:     hidden_block_count_z
      - .offset:         164
        .size:           2
        .value_kind:     hidden_group_size_x
      - .offset:         166
        .size:           2
        .value_kind:     hidden_group_size_y
      - .offset:         168
        .size:           2
        .value_kind:     hidden_group_size_z
      - .offset:         170
        .size:           2
        .value_kind:     hidden_remainder_x
      - .offset:         172
        .size:           2
        .value_kind:     hidden_remainder_y
      - .offset:         174
        .size:           2
        .value_kind:     hidden_remainder_z
      - .offset:         192
        .size:           8
        .value_kind:     hidden_global_offset_x
      - .offset:         200
        .size:           8
        .value_kind:     hidden_global_offset_y
      - .offset:         208
        .size:           8
        .value_kind:     hidden_global_offset_z
      - .offset:         216
        .size:           2
        .value_kind:     hidden_grid_dims
      - .offset:         240
        .size:           8
        .value_kind:     hidden_multigrid_sync_arg
      - .offset:         272
        .size:           4
        .value_kind:     hidden_dynamic_lds_size
    .group_segment_fixed_size: 0
    .kernarg_segment_align: 8
    .kernarg_segment_size: 408
    .language:       OpenCL C
    .language_version:
      - 2
      - 0
    .max_flat_workgroup_size: 512
    .name:           _Z8mega_fwd6Params
    .private_segment_fixed_size: 0
    .sgpr_count:     104
    .sgpr_spill_count: 75
    .symbol:         _Z8mega_fwd6Params.kd
    .uniform_work_group_size: 1
    .uses_dynamic_stack: false
    .vgpr_count:     256
    .vgpr_spill_count: 0
    .wavefront_size: 64
